# v87 + windowed packed-f32 peephole (pkpeep2): 256 mul/add pairs packed in the two in-proj rope epilogue blocks (critical path), 35 elsewhere
# speedup vs baseline: 1.0084x; 1.0084x over previous
; __device__ __forceinline__ u32x4 pack8(const float (&v)[8]) { u32x4 w; w.x = pk2(v[0], v[1]); w.y = pk2(v[2], v[3]); w.z = pk2(v[4], v[5]); w.w = pk2(v[6], v[7]); return w; }
;     __device__ __forceinline__ bool operator()(Acc& acc, const Unit& u, int wr, int wc, int fr, int fq, const LAS float* rstab) const {
;     ...
;                 if (rope) {
;                     const float sgn = (fq == 0) ? -1.f : 1.f;
; #pragma unroll
;                     for (int ai = 0; ai < 2; ++ai)
; #pragma unroll
;                         for (int m = 0; m < 4; ++m) {
;                             const float rs = rsp[ai * HALF + m * 16] * scale;
;                             const int pos = (rowb + ai * HALF + m * 16) & (SEQ - 1);
;                             const f32x4 c0 = gld<f32x4>(ropec + pos * 8), c1 = gld<f32x4>(ropec + pos * 8 + 4);
;                             const f32x4 s0 = gld<f32x4>(ropes + pos * 8), s1 = gld<f32x4>(ropes + pos * 8 + 4);
;                             float v[8];
; #pragma unroll
;                             for (int e = 0; e < 4; ++e) { v[e] = acc[ai][bj][m][0][e] * rs; v[4 + e] = acc[ai][bj][m][1][e] * rs; }
; #pragma unroll
;                             for (int e = 0; e < 8; ++e) {
;                                 const float p = __shfl_xor(v[e], 16);
;                                 const float cs = e < 4 ? c0[e & 3] : c1[e & 3], sn = e < 4 ? s0[e & 3] : s1[e & 3];
;                                 const float r = v[e] * cs + sgn * p * sn;
;                                 v[e] = (fq < 2) ? r : v[e];
;                             }
;                             gst<u32x4>(p0 + (ai * HALF + m * 16) * pitch, pack8(v));
;                             asm volatile("" ::: "memory");
;                         }
.LBB0_419:
	s_andn2_b64 vcc, exec, s[60:61]
	s_cbranch_vccnz .LBB0_421
	v_and_b32_e32 v132, 64, v198
	v_xor_b32_e32 v0, 16, v198
	v_add_u32_e32 v132, 64, v132
	v_cmp_lt_i32_e32 vcc, v0, v132
	s_lshl_b32 s26, s71, 5
	s_mov_b32 s59, s27
	s_mov_b32 s19, s27
	s_mov_b32 s17, s27
	s_mov_b32 s15, s27
	v_cndmask_b32_e32 v0, v198, v0, vcc
	v_lshlrev_b32_e32 v0, 2, v0
	ds_read_b32 v188, v154
	v_lshlrev_b32_e32 v159, 5, v2
	v_and_b32_e32 v159, 0xf9e0, v159
	global_load_dwordx4 v[164:167], v159, s[20:21] offset:16
	global_load_dwordx4 v[160:163], v159, s[20:21]
	global_load_dwordx4 v[172:175], v159, s[22:23] offset:16
	global_load_dwordx4 v[168:171], v159, s[22:23]
	s_waitcnt lgkmcnt(0)
	v_mul_f32_e32 v188, s9, v188
	v_pk_mul_f32 v[212:213], v[120:121], v[188:189] op_sel_hi:[1,0]
	v_pk_mul_f32 v[214:215], v[122:123], v[188:189] op_sel_hi:[1,0]
	v_pk_mul_f32 v[216:217], v[112:113], v[188:189] op_sel_hi:[1,0]
	v_pk_mul_f32 v[218:219], v[114:115], v[188:189] op_sel_hi:[1,0]
	ds_bpermute_b32 v228, v0, v212
	ds_bpermute_b32 v229, v0, v213
	ds_bpermute_b32 v230, v0, v214
	ds_bpermute_b32 v231, v0, v215
	ds_bpermute_b32 v132, v0, v216
	ds_bpermute_b32 v133, v0, v217
	ds_bpermute_b32 v134, v0, v218
	ds_bpermute_b32 v135, v0, v219
	ds_read_b32 v189, v154 offset:64
	v_or_b32_e32 v143, 0x200, v159
	global_load_dwordx4 v[180:183], v143, s[20:21] offset:16
	global_load_dwordx4 v[176:179], v143, s[20:21]
	global_load_dwordx4 v[190:193], v143, s[22:23] offset:16
	global_load_dwordx4 v[184:187], v143, s[22:23]
	s_waitcnt lgkmcnt(1)
	s_waitcnt vmcnt(4)
	v_cndmask_b32_e64 v228, v228, -v228, s[56:57]
	v_cndmask_b32_e64 v229, v229, -v229, s[56:57]
	v_cndmask_b32_e64 v230, v230, -v230, s[56:57]
	v_cndmask_b32_e64 v231, v231, -v231, s[56:57]
	v_cndmask_b32_e64 v132, v132, -v132, s[56:57]
	v_cndmask_b32_e64 v133, v133, -v133, s[56:57]
	v_cndmask_b32_e64 v134, v134, -v134, s[56:57]
	v_cndmask_b32_e64 v135, v135, -v135, s[56:57]
	v_pk_mul_f32 v[160:161], v[212:213], v[160:161]
	v_pk_mul_f32 v[162:163], v[214:215], v[162:163]
	v_pk_mul_f32 v[164:165], v[216:217], v[164:165]
	v_pk_mul_f32 v[166:167], v[218:219], v[166:167]
	v_pk_mul_f32 v[168:169], v[228:229], v[168:169]
	v_pk_mul_f32 v[170:171], v[230:231], v[170:171]
	v_pk_mul_f32 v[172:173], v[132:133], v[172:173]
	v_pk_mul_f32 v[174:175], v[134:135], v[174:175]
	v_pk_add_f32 v[160:161], v[160:161], v[168:169]
	v_pk_add_f32 v[162:163], v[162:163], v[170:171]
	v_pk_add_f32 v[164:165], v[164:165], v[172:173]
	v_pk_add_f32 v[166:167], v[166:167], v[174:175]
	v_cndmask_b32_e64 v212, v212, v160, s[54:55]
	v_cndmask_b32_e64 v213, v213, v161, s[54:55]
	v_cndmask_b32_e64 v214, v214, v162, s[54:55]
	v_cndmask_b32_e64 v215, v215, v163, s[54:55]
	v_cndmask_b32_e64 v216, v216, v164, s[54:55]
	v_cndmask_b32_e64 v217, v217, v165, s[54:55]
	v_cndmask_b32_e64 v218, v218, v166, s[54:55]
	v_cndmask_b32_e64 v219, v219, v167, s[54:55]
	v_cvt_pk_bf16_f32 v228, v212, v213
	v_cvt_pk_bf16_f32 v229, v214, v215
	v_cvt_pk_bf16_f32 v230, v216, v217
	v_cvt_pk_bf16_f32 v231, v218, v219
	global_store_dwordx4 v[140:141], v[228:231], off
	s_waitcnt lgkmcnt(0)
	v_mul_f32_e32 v189, s9, v189
	v_pk_mul_f32 v[212:213], v[100:101], v[188:189] op_sel:[0,1]
	v_pk_mul_f32 v[214:215], v[102:103], v[188:189] op_sel:[0,1]
	v_pk_mul_f32 v[216:217], v[88:89], v[188:189] op_sel:[0,1]
	v_pk_mul_f32 v[218:219], v[90:91], v[188:189] op_sel:[0,1]
	ds_bpermute_b32 v228, v0, v212
	ds_bpermute_b32 v229, v0, v213
	ds_bpermute_b32 v230, v0, v214
	ds_bpermute_b32 v231, v0, v215
	ds_bpermute_b32 v132, v0, v216
	ds_bpermute_b32 v133, v0, v217
	ds_bpermute_b32 v134, v0, v218
	ds_bpermute_b32 v135, v0, v219
	ds_read_b32 v188, v154 offset:128
	v_or_b32_e32 v143, 0x400, v159
	global_load_dwordx4 v[164:167], v143, s[20:21] offset:16
	global_load_dwordx4 v[160:163], v143, s[20:21]
	global_load_dwordx4 v[172:175], v143, s[22:23] offset:16
	global_load_dwordx4 v[168:171], v143, s[22:23]
	s_waitcnt lgkmcnt(1)
	s_waitcnt vmcnt(5)
	v_cndmask_b32_e64 v228, v228, -v228, s[56:57]
	v_cndmask_b32_e64 v229, v229, -v229, s[56:57]
	v_cndmask_b32_e64 v230, v230, -v230, s[56:57]
	v_cndmask_b32_e64 v231, v231, -v231, s[56:57]
	v_cndmask_b32_e64 v132, v132, -v132, s[56:57]
	v_cndmask_b32_e64 v133, v133, -v133, s[56:57]
	v_cndmask_b32_e64 v134, v134, -v134, s[56:57]
	v_cndmask_b32_e64 v135, v135, -v135, s[56:57]
	v_pk_mul_f32 v[176:177], v[212:213], v[176:177]
	v_pk_mul_f32 v[178:179], v[214:215], v[178:179]
	v_pk_mul_f32 v[180:181], v[216:217], v[180:181]
	v_pk_mul_f32 v[182:183], v[218:219], v[182:183]
	v_pk_mul_f32 v[184:185], v[228:229], v[184:185]
	v_pk_mul_f32 v[186:187], v[230:231], v[186:187]
	v_pk_mul_f32 v[190:191], v[132:133], v[190:191]
	v_pk_mul_f32 v[192:193], v[134:135], v[192:193]
	v_pk_add_f32 v[176:177], v[176:177], v[184:185]
	v_pk_add_f32 v[178:179], v[178:179], v[186:187]
	v_pk_add_f32 v[180:181], v[180:181], v[190:191]
	v_pk_add_f32 v[182:183], v[182:183], v[192:193]
	v_cndmask_b32_e64 v212, v212, v176, s[54:55]
	v_cndmask_b32_e64 v213, v213, v177, s[54:55]
	v_cndmask_b32_e64 v214, v214, v178, s[54:55]
	v_cndmask_b32_e64 v215, v215, v179, s[54:55]
	v_cndmask_b32_e64 v216, v216, v180, s[54:55]
	v_cndmask_b32_e64 v217, v217, v181, s[54:55]
	v_cndmask_b32_e64 v218, v218, v182, s[54:55]
	v_cndmask_b32_e64 v219, v219, v183, s[54:55]
	v_cvt_pk_bf16_f32 v228, v212, v213
	v_cvt_pk_bf16_f32 v229, v214, v215
	v_cvt_pk_bf16_f32 v230, v216, v217
	v_cvt_pk_bf16_f32 v231, v218, v219
	v_lshl_add_u64 v[132:133], v[140:141], 0, s[26:27]
	global_store_dwordx4 v[132:133], v[228:231], off
	s_waitcnt lgkmcnt(0)
; __device__ __forceinline__ u32x4 pack8(const float (&v)[8]) { u32x4 w; w.x = pk2(v[0], v[1]); w.y = pk2(v[2], v[3]); w.z = pk2(v[4], v[5]); w.w = pk2(v[6], v[7]); return w; }
;     __device__ __forceinline__ bool operator()(Acc& acc, const Unit& u, int wr, int wc, int fr, int fq, const LAS float* rstab) const {
;     ...
;                 if (rope) {
;                     const float sgn = (fq == 0) ? -1.f : 1.f;
; #pragma unroll
;                     for (int ai = 0; ai < 2; ++ai)
; #pragma unroll
;                         for (int m = 0; m < 4; ++m) {
;                             const float rs = rsp[ai * HALF + m * 16] * scale;
;                             const int pos = (rowb + ai * HALF + m * 16) & (SEQ - 1);
;                             const f32x4 c0 = gld<f32x4>(ropec + pos * 8), c1 = gld<f32x4>(ropec + pos * 8 + 4);
;                             const f32x4 s0 = gld<f32x4>(ropes + pos * 8), s1 = gld<f32x4>(ropes + pos * 8 + 4);
;                             float v[8];
; #pragma unroll
;                             for (int e = 0; e < 4; ++e) { v[e] = acc[ai][bj][m][0][e] * rs; v[4 + e] = acc[ai][bj][m][1][e] * rs; }
; #pragma unroll
;                             for (int e = 0; e < 8; ++e) {
;                                 const float p = __shfl_xor(v[e], 16);
;                                 const float cs = e < 4 ? c0[e & 3] : c1[e & 3], sn = e < 4 ? s0[e & 3] : s1[e & 3];
;                                 const float r = v[e] * cs + sgn * p * sn;
;                                 v[e] = (fq < 2) ? r : v[e];
;                             }
;                             gst<u32x4>(p0 + (ai * HALF + m * 16) * pitch, pack8(v));
;                             asm volatile("" ::: "memory");
;                         }
	v_mul_f32_e32 v188, s9, v188
	v_pk_mul_f32 v[212:213], v[68:69], v[188:189] op_sel_hi:[1,0]
	v_pk_mul_f32 v[214:215], v[70:71], v[188:189] op_sel_hi:[1,0]
	v_pk_mul_f32 v[216:217], v[56:57], v[188:189] op_sel_hi:[1,0]
	v_pk_mul_f32 v[218:219], v[58:59], v[188:189] op_sel_hi:[1,0]
	ds_bpermute_b32 v228, v0, v212
	ds_bpermute_b32 v229, v0, v213
	ds_bpermute_b32 v230, v0, v214
	ds_bpermute_b32 v231, v0, v215
	ds_bpermute_b32 v132, v0, v216
	ds_bpermute_b32 v133, v0, v217
	ds_bpermute_b32 v134, v0, v218
	ds_bpermute_b32 v135, v0, v219
	ds_read_b32 v189, v154 offset:192
	v_or_b32_e32 v143, 0x600, v159
	global_load_dwordx4 v[180:183], v143, s[20:21] offset:16
	global_load_dwordx4 v[176:179], v143, s[20:21]
	global_load_dwordx4 v[190:193], v143, s[22:23] offset:16
	global_load_dwordx4 v[184:187], v143, s[22:23]
	s_waitcnt lgkmcnt(1)
	s_waitcnt vmcnt(5)
	v_cndmask_b32_e64 v228, v228, -v228, s[56:57]
	v_cndmask_b32_e64 v229, v229, -v229, s[56:57]
	v_cndmask_b32_e64 v230, v230, -v230, s[56:57]
	v_cndmask_b32_e64 v231, v231, -v231, s[56:57]
	v_cndmask_b32_e64 v132, v132, -v132, s[56:57]
	v_cndmask_b32_e64 v133, v133, -v133, s[56:57]
	v_cndmask_b32_e64 v134, v134, -v134, s[56:57]
	v_cndmask_b32_e64 v135, v135, -v135, s[56:57]
	v_pk_mul_f32 v[160:161], v[212:213], v[160:161]
	v_pk_mul_f32 v[162:163], v[214:215], v[162:163]
	v_pk_mul_f32 v[164:165], v[216:217], v[164:165]
	v_pk_mul_f32 v[166:167], v[218:219], v[166:167]
	v_pk_mul_f32 v[168:169], v[228:229], v[168:169]
	v_pk_mul_f32 v[170:171], v[230:231], v[170:171]
	v_pk_mul_f32 v[172:173], v[132:133], v[172:173]
	v_pk_mul_f32 v[174:175], v[134:135], v[174:175]
	v_pk_add_f32 v[160:161], v[160:161], v[168:169]
	v_pk_add_f32 v[162:163], v[162:163], v[170:171]
	v_pk_add_f32 v[164:165], v[164:165], v[172:173]
	v_pk_add_f32 v[166:167], v[166:167], v[174:175]
	v_cndmask_b32_e64 v212, v212, v160, s[54:55]
	v_cndmask_b32_e64 v213, v213, v161, s[54:55]
	v_cndmask_b32_e64 v214, v214, v162, s[54:55]
	v_cndmask_b32_e64 v215, v215, v163, s[54:55]
	v_cndmask_b32_e64 v216, v216, v164, s[54:55]
	v_cndmask_b32_e64 v217, v217, v165, s[54:55]
	v_cndmask_b32_e64 v218, v218, v166, s[54:55]
	v_cndmask_b32_e64 v219, v219, v167, s[54:55]
	v_cvt_pk_bf16_f32 v228, v212, v213
	v_cvt_pk_bf16_f32 v229, v214, v215
	v_cvt_pk_bf16_f32 v230, v216, v217
	v_cvt_pk_bf16_f32 v231, v218, v219
	v_lshl_add_u64 v[132:133], s[26:27], 1, v[140:141]
	global_store_dwordx4 v[132:133], v[228:231], off
	s_lshl_b32 s26, s71, 8
	s_waitcnt lgkmcnt(0)
	v_mul_f32_e32 v189, s9, v189
	v_pk_mul_f32 v[212:213], v[36:37], v[188:189] op_sel:[0,1]
	v_pk_mul_f32 v[214:215], v[38:39], v[188:189] op_sel:[0,1]
	v_pk_mul_f32 v[216:217], v[28:29], v[188:189] op_sel:[0,1]
	v_pk_mul_f32 v[218:219], v[30:31], v[188:189] op_sel:[0,1]
	ds_bpermute_b32 v228, v0, v212
	ds_bpermute_b32 v229, v0, v213
	ds_bpermute_b32 v230, v0, v214
	ds_bpermute_b32 v231, v0, v215
	ds_bpermute_b32 v132, v0, v216
	ds_bpermute_b32 v133, v0, v217
	ds_bpermute_b32 v134, v0, v218
	ds_bpermute_b32 v135, v0, v219
	ds_read_b32 v188, v154 offset:512
	v_mov_b32_e32 v159, 0x400
	v_lshl_add_u32 v159, v2, 3, v159
	v_and_b32_e32 v159, 0x3e78, v159
	v_lshlrev_b32_e32 v159, 2, v159
	global_load_dwordx4 v[164:167], v159, s[20:21] offset:16
	global_load_dwordx4 v[160:163], v159, s[20:21]
	global_load_dwordx4 v[172:175], v159, s[22:23] offset:16
	global_load_dwordx4 v[168:171], v159, s[22:23]
	s_waitcnt lgkmcnt(1)
	s_waitcnt vmcnt(5)
	v_cndmask_b32_e64 v228, v228, -v228, s[56:57]
	v_cndmask_b32_e64 v229, v229, -v229, s[56:57]
	v_cndmask_b32_e64 v230, v230, -v230, s[56:57]
	v_cndmask_b32_e64 v231, v231, -v231, s[56:57]
	v_cndmask_b32_e64 v132, v132, -v132, s[56:57]
	v_cndmask_b32_e64 v133, v133, -v133, s[56:57]
	v_cndmask_b32_e64 v134, v134, -v134, s[56:57]
	v_cndmask_b32_e64 v135, v135, -v135, s[56:57]
	v_pk_mul_f32 v[176:177], v[212:213], v[176:177]
	v_pk_mul_f32 v[178:179], v[214:215], v[178:179]
	v_pk_mul_f32 v[180:181], v[216:217], v[180:181]
	v_pk_mul_f32 v[182:183], v[218:219], v[182:183]
	v_pk_mul_f32 v[184:185], v[228:229], v[184:185]
	v_pk_mul_f32 v[186:187], v[230:231], v[186:187]
	v_pk_mul_f32 v[190:191], v[132:133], v[190:191]
	v_pk_mul_f32 v[192:193], v[134:135], v[192:193]
	v_pk_add_f32 v[176:177], v[176:177], v[184:185]
	v_pk_add_f32 v[178:179], v[178:179], v[186:187]
	v_pk_add_f32 v[180:181], v[180:181], v[190:191]
	v_pk_add_f32 v[182:183], v[182:183], v[192:193]
	v_cndmask_b32_e64 v212, v212, v176, s[54:55]
	v_cndmask_b32_e64 v213, v213, v177, s[54:55]
	v_cndmask_b32_e64 v214, v214, v178, s[54:55]
	v_cndmask_b32_e64 v215, v215, v179, s[54:55]
	v_cndmask_b32_e64 v216, v216, v180, s[54:55]
	v_cndmask_b32_e64 v217, v217, v181, s[54:55]
	v_cndmask_b32_e64 v218, v218, v182, s[54:55]
	v_cndmask_b32_e64 v219, v219, v183, s[54:55]
	v_cvt_pk_bf16_f32 v228, v212, v213
	v_cvt_pk_bf16_f32 v229, v214, v215
	v_cvt_pk_bf16_f32 v230, v216, v217
	v_cvt_pk_bf16_f32 v231, v218, v219
	v_lshl_add_u64 v[132:133], s[58:59], 1, v[140:141]
	global_store_dwordx4 v[132:133], v[228:231], off
	s_waitcnt lgkmcnt(0)
	v_mul_f32_e32 v188, s9, v188
	v_pk_mul_f32 v[212:213], v[72:73], v[188:189] op_sel_hi:[1,0]
	v_pk_mul_f32 v[214:215], v[74:75], v[188:189] op_sel_hi:[1,0]
	v_pk_mul_f32 v[216:217], v[60:61], v[188:189] op_sel_hi:[1,0]
	v_pk_mul_f32 v[218:219], v[62:63], v[188:189] op_sel_hi:[1,0]
	ds_bpermute_b32 v228, v0, v212
	ds_bpermute_b32 v229, v0, v213
	ds_bpermute_b32 v230, v0, v214
	ds_bpermute_b32 v231, v0, v215
	ds_bpermute_b32 v132, v0, v216
	ds_bpermute_b32 v133, v0, v217
	ds_bpermute_b32 v134, v0, v218
	ds_bpermute_b32 v135, v0, v219
	ds_read_b32 v189, v154 offset:576
	v_or_b32_e32 v143, 0x200, v159
	global_load_dwordx4 v[180:183], v143, s[20:21] offset:16
	global_load_dwordx4 v[176:179], v143, s[20:21]
	global_load_dwordx4 v[190:193], v143, s[22:23] offset:16
	global_load_dwordx4 v[184:187], v143, s[22:23]
	s_waitcnt lgkmcnt(1)
; __device__ __forceinline__ u32x4 pack8(const float (&v)[8]) { u32x4 w; w.x = pk2(v[0], v[1]); w.y = pk2(v[2], v[3]); w.z = pk2(v[4], v[5]); w.w = pk2(v[6], v[7]); return w; }
;     __device__ __forceinline__ bool operator()(Acc& acc, const Unit& u, int wr, int wc, int fr, int fq, const LAS float* rstab) const {
;     ...
;                 if (rope) {
;                     const float sgn = (fq == 0) ? -1.f : 1.f;
; #pragma unroll
;                     for (int ai = 0; ai < 2; ++ai)
; #pragma unroll
;                         for (int m = 0; m < 4; ++m) {
;                             const float rs = rsp[ai * HALF + m * 16] * scale;
;                             const int pos = (rowb + ai * HALF + m * 16) & (SEQ - 1);
;                             const f32x4 c0 = gld<f32x4>(ropec + pos * 8), c1 = gld<f32x4>(ropec + pos * 8 + 4);
;                             const f32x4 s0 = gld<f32x4>(ropes + pos * 8), s1 = gld<f32x4>(ropes + pos * 8 + 4);
;                             float v[8];
; #pragma unroll
;                             for (int e = 0; e < 4; ++e) { v[e] = acc[ai][bj][m][0][e] * rs; v[4 + e] = acc[ai][bj][m][1][e] * rs; }
; #pragma unroll
;                             for (int e = 0; e < 8; ++e) {
;                                 const float p = __shfl_xor(v[e], 16);
;                                 const float cs = e < 4 ? c0[e & 3] : c1[e & 3], sn = e < 4 ? s0[e & 3] : s1[e & 3];
;                                 const float r = v[e] * cs + sgn * p * sn;
;                                 v[e] = (fq < 2) ? r : v[e];
;                             }
;                             gst<u32x4>(p0 + (ai * HALF + m * 16) * pitch, pack8(v));
;                             asm volatile("" ::: "memory");
;                         }
	s_waitcnt vmcnt(5)
	v_cndmask_b32_e64 v228, v228, -v228, s[56:57]
	v_cndmask_b32_e64 v229, v229, -v229, s[56:57]
	v_cndmask_b32_e64 v230, v230, -v230, s[56:57]
	v_cndmask_b32_e64 v231, v231, -v231, s[56:57]
	v_cndmask_b32_e64 v132, v132, -v132, s[56:57]
	v_cndmask_b32_e64 v133, v133, -v133, s[56:57]
	v_cndmask_b32_e64 v134, v134, -v134, s[56:57]
	v_cndmask_b32_e64 v135, v135, -v135, s[56:57]
	v_pk_mul_f32 v[160:161], v[212:213], v[160:161]
	v_pk_mul_f32 v[162:163], v[214:215], v[162:163]
	v_pk_mul_f32 v[164:165], v[216:217], v[164:165]
	v_pk_mul_f32 v[166:167], v[218:219], v[166:167]
	v_pk_mul_f32 v[168:169], v[228:229], v[168:169]
	v_pk_mul_f32 v[170:171], v[230:231], v[170:171]
	v_pk_mul_f32 v[172:173], v[132:133], v[172:173]
	v_pk_mul_f32 v[174:175], v[134:135], v[174:175]
	v_pk_add_f32 v[160:161], v[160:161], v[168:169]
	v_pk_add_f32 v[162:163], v[162:163], v[170:171]
	v_pk_add_f32 v[164:165], v[164:165], v[172:173]
	v_pk_add_f32 v[166:167], v[166:167], v[174:175]
	v_cndmask_b32_e64 v212, v212, v160, s[54:55]
	v_cndmask_b32_e64 v213, v213, v161, s[54:55]
	v_cndmask_b32_e64 v214, v214, v162, s[54:55]
	v_cndmask_b32_e64 v215, v215, v163, s[54:55]
	v_cndmask_b32_e64 v216, v216, v164, s[54:55]
	v_cndmask_b32_e64 v217, v217, v165, s[54:55]
	v_cndmask_b32_e64 v218, v218, v166, s[54:55]
	v_cndmask_b32_e64 v219, v219, v167, s[54:55]
	v_cvt_pk_bf16_f32 v228, v212, v213
	v_cvt_pk_bf16_f32 v229, v214, v215
	v_cvt_pk_bf16_f32 v230, v216, v217
	v_cvt_pk_bf16_f32 v231, v218, v219
	v_lshl_add_u64 v[132:133], v[140:141], 0, s[26:27]
	global_store_dwordx4 v[132:133], v[228:231], off
	s_waitcnt lgkmcnt(0)
	v_mul_f32_e32 v189, s9, v189
	v_pk_mul_f32 v[212:213], v[40:41], v[188:189] op_sel:[0,1]
	v_pk_mul_f32 v[214:215], v[42:43], v[188:189] op_sel:[0,1]
	v_pk_mul_f32 v[216:217], v[32:33], v[188:189] op_sel:[0,1]
	v_pk_mul_f32 v[218:219], v[34:35], v[188:189] op_sel:[0,1]
	ds_bpermute_b32 v228, v0, v212
	ds_bpermute_b32 v229, v0, v213
	ds_bpermute_b32 v230, v0, v214
	ds_bpermute_b32 v231, v0, v215
	ds_bpermute_b32 v132, v0, v216
	ds_bpermute_b32 v133, v0, v217
	ds_bpermute_b32 v134, v0, v218
	ds_bpermute_b32 v135, v0, v219
	ds_read_b32 v188, v154 offset:640
	v_or_b32_e32 v143, 0x400, v159
	global_load_dwordx4 v[164:167], v143, s[20:21] offset:16
	global_load_dwordx4 v[160:163], v143, s[20:21]
	global_load_dwordx4 v[172:175], v143, s[22:23] offset:16
	global_load_dwordx4 v[168:171], v143, s[22:23]
	s_waitcnt lgkmcnt(1)
	s_waitcnt vmcnt(5)
	v_cndmask_b32_e64 v228, v228, -v228, s[56:57]
	v_cndmask_b32_e64 v229, v229, -v229, s[56:57]
	v_cndmask_b32_e64 v230, v230, -v230, s[56:57]
	v_cndmask_b32_e64 v231, v231, -v231, s[56:57]
	v_cndmask_b32_e64 v132, v132, -v132, s[56:57]
	v_cndmask_b32_e64 v133, v133, -v133, s[56:57]
	v_cndmask_b32_e64 v134, v134, -v134, s[56:57]
	v_cndmask_b32_e64 v135, v135, -v135, s[56:57]
	v_pk_mul_f32 v[176:177], v[212:213], v[176:177]
	v_pk_mul_f32 v[178:179], v[214:215], v[178:179]
	v_pk_mul_f32 v[180:181], v[216:217], v[180:181]
	v_pk_mul_f32 v[182:183], v[218:219], v[182:183]
	v_pk_mul_f32 v[184:185], v[228:229], v[184:185]
	v_pk_mul_f32 v[186:187], v[230:231], v[186:187]
	v_pk_mul_f32 v[190:191], v[132:133], v[190:191]
	v_pk_mul_f32 v[192:193], v[134:135], v[192:193]
	v_pk_add_f32 v[176:177], v[176:177], v[184:185]
	v_pk_add_f32 v[178:179], v[178:179], v[186:187]
	v_pk_add_f32 v[180:181], v[180:181], v[190:191]
	v_pk_add_f32 v[182:183], v[182:183], v[192:193]
	v_cndmask_b32_e64 v212, v212, v176, s[54:55]
	v_cndmask_b32_e64 v213, v213, v177, s[54:55]
	v_cndmask_b32_e64 v214, v214, v178, s[54:55]
	v_cndmask_b32_e64 v215, v215, v179, s[54:55]
	v_cndmask_b32_e64 v216, v216, v180, s[54:55]
	v_cndmask_b32_e64 v217, v217, v181, s[54:55]
	v_cndmask_b32_e64 v218, v218, v182, s[54:55]
	v_cndmask_b32_e64 v219, v219, v183, s[54:55]
	v_cvt_pk_bf16_f32 v228, v212, v213
	v_cvt_pk_bf16_f32 v229, v214, v215
	v_cvt_pk_bf16_f32 v230, v216, v217
	v_cvt_pk_bf16_f32 v231, v218, v219
	v_lshl_add_u64 v[132:133], s[18:19], 1, v[140:141]
	global_store_dwordx4 v[132:133], v[228:231], off
	s_waitcnt lgkmcnt(0)
; __device__ __forceinline__ u32x4 pack8(const float (&v)[8]) { u32x4 w; w.x = pk2(v[0], v[1]); w.y = pk2(v[2], v[3]); w.z = pk2(v[4], v[5]); w.w = pk2(v[6], v[7]); return w; }
;     __device__ __forceinline__ bool operator()(Acc& acc, const Unit& u, int wr, int wc, int fr, int fq, const LAS float* rstab) const {
;     ...
;                 if (rope) {
;                     const float sgn = (fq == 0) ? -1.f : 1.f;
; #pragma unroll
;                     for (int ai = 0; ai < 2; ++ai)
; #pragma unroll
;                         for (int m = 0; m < 4; ++m) {
;                             const float rs = rsp[ai * HALF + m * 16] * scale;
;                             const int pos = (rowb + ai * HALF + m * 16) & (SEQ - 1);
;                             const f32x4 c0 = gld<f32x4>(ropec + pos * 8), c1 = gld<f32x4>(ropec + pos * 8 + 4);
;                             const f32x4 s0 = gld<f32x4>(ropes + pos * 8), s1 = gld<f32x4>(ropes + pos * 8 + 4);
;                             float v[8];
; #pragma unroll
;                             for (int e = 0; e < 4; ++e) { v[e] = acc[ai][bj][m][0][e] * rs; v[4 + e] = acc[ai][bj][m][1][e] * rs; }
; #pragma unroll
;                             for (int e = 0; e < 8; ++e) {
;                                 const float p = __shfl_xor(v[e], 16);
;                                 const float cs = e < 4 ? c0[e & 3] : c1[e & 3], sn = e < 4 ? s0[e & 3] : s1[e & 3];
;                                 const float r = v[e] * cs + sgn * p * sn;
;                                 v[e] = (fq < 2) ? r : v[e];
;                             }
;                             gst<u32x4>(p0 + (ai * HALF + m * 16) * pitch, pack8(v));
;                             asm volatile("" ::: "memory");
;                         }
	v_mul_f32_e32 v188, s9, v188
	v_pk_mul_f32 v[212:213], v[16:17], v[188:189] op_sel_hi:[1,0]
	v_pk_mul_f32 v[214:215], v[18:19], v[188:189] op_sel_hi:[1,0]
	v_pk_mul_f32 v[216:217], v[12:13], v[188:189] op_sel_hi:[1,0]
	v_pk_mul_f32 v[218:219], v[14:15], v[188:189] op_sel_hi:[1,0]
	ds_bpermute_b32 v228, v0, v212
	ds_bpermute_b32 v229, v0, v213
	ds_bpermute_b32 v230, v0, v214
	ds_bpermute_b32 v231, v0, v215
	ds_bpermute_b32 v132, v0, v216
	ds_bpermute_b32 v133, v0, v217
	ds_bpermute_b32 v134, v0, v218
	ds_bpermute_b32 v135, v0, v219
	ds_read_b32 v189, v154 offset:704
	v_or_b32_e32 v143, 0x600, v159
	global_load_dwordx4 v[180:183], v143, s[20:21] offset:16
	global_load_dwordx4 v[176:179], v143, s[20:21]
	global_load_dwordx4 v[190:193], v143, s[22:23] offset:16
	global_load_dwordx4 v[184:187], v143, s[22:23]
	s_waitcnt lgkmcnt(1)
	s_waitcnt vmcnt(5)
	v_cndmask_b32_e64 v228, v228, -v228, s[56:57]
	v_cndmask_b32_e64 v229, v229, -v229, s[56:57]
	v_cndmask_b32_e64 v230, v230, -v230, s[56:57]
	v_cndmask_b32_e64 v231, v231, -v231, s[56:57]
	v_cndmask_b32_e64 v132, v132, -v132, s[56:57]
	v_cndmask_b32_e64 v133, v133, -v133, s[56:57]
	v_cndmask_b32_e64 v134, v134, -v134, s[56:57]
	v_cndmask_b32_e64 v135, v135, -v135, s[56:57]
	v_pk_mul_f32 v[160:161], v[212:213], v[160:161]
	v_pk_mul_f32 v[162:163], v[214:215], v[162:163]
	v_pk_mul_f32 v[164:165], v[216:217], v[164:165]
	v_pk_mul_f32 v[166:167], v[218:219], v[166:167]
	v_pk_mul_f32 v[168:169], v[228:229], v[168:169]
	v_pk_mul_f32 v[170:171], v[230:231], v[170:171]
	v_pk_mul_f32 v[172:173], v[132:133], v[172:173]
	v_pk_mul_f32 v[174:175], v[134:135], v[174:175]
	v_pk_add_f32 v[160:161], v[160:161], v[168:169]
	v_pk_add_f32 v[162:163], v[162:163], v[170:171]
	v_pk_add_f32 v[164:165], v[164:165], v[172:173]
	v_pk_add_f32 v[166:167], v[166:167], v[174:175]
	v_cndmask_b32_e64 v212, v212, v160, s[54:55]
	v_cndmask_b32_e64 v213, v213, v161, s[54:55]
	v_cndmask_b32_e64 v214, v214, v162, s[54:55]
	v_cndmask_b32_e64 v215, v215, v163, s[54:55]
	v_cndmask_b32_e64 v216, v216, v164, s[54:55]
	v_cndmask_b32_e64 v217, v217, v165, s[54:55]
	v_cndmask_b32_e64 v218, v218, v166, s[54:55]
	v_cndmask_b32_e64 v219, v219, v167, s[54:55]
	v_cvt_pk_bf16_f32 v228, v212, v213
	v_cvt_pk_bf16_f32 v229, v214, v215
	v_cvt_pk_bf16_f32 v230, v216, v217
	v_cvt_pk_bf16_f32 v231, v218, v219
	v_lshl_add_u64 v[132:133], s[16:17], 1, v[140:141]
	global_store_dwordx4 v[132:133], v[228:231], off
	s_waitcnt lgkmcnt(0)
	v_mul_f32_e32 v189, s9, v189
	v_pk_mul_f32 v[212:213], v[8:9], v[188:189] op_sel:[0,1]
	v_pk_mul_f32 v[214:215], v[10:11], v[188:189] op_sel:[0,1]
	v_pk_mul_f32 v[216:217], v[4:5], v[188:189] op_sel:[0,1]
	v_pk_mul_f32 v[218:219], v[6:7], v[188:189] op_sel:[0,1]
	ds_bpermute_b32 v228, v0, v212
	ds_bpermute_b32 v229, v0, v213
	ds_bpermute_b32 v230, v0, v214
	ds_bpermute_b32 v231, v0, v215
	ds_bpermute_b32 v132, v0, v216
	ds_bpermute_b32 v133, v0, v217
	ds_bpermute_b32 v134, v0, v218
	ds_bpermute_b32 v135, v0, v219
	s_waitcnt lgkmcnt(0)
	s_waitcnt vmcnt(1)
	v_cndmask_b32_e64 v228, v228, -v228, s[56:57]
	v_cndmask_b32_e64 v229, v229, -v229, s[56:57]
	v_cndmask_b32_e64 v230, v230, -v230, s[56:57]
	v_cndmask_b32_e64 v231, v231, -v231, s[56:57]
	v_cndmask_b32_e64 v132, v132, -v132, s[56:57]
	v_cndmask_b32_e64 v133, v133, -v133, s[56:57]
	v_cndmask_b32_e64 v134, v134, -v134, s[56:57]
	v_cndmask_b32_e64 v135, v135, -v135, s[56:57]
	v_pk_mul_f32 v[176:177], v[212:213], v[176:177]
	v_pk_mul_f32 v[178:179], v[214:215], v[178:179]
	v_pk_mul_f32 v[180:181], v[216:217], v[180:181]
	v_pk_mul_f32 v[182:183], v[218:219], v[182:183]
	v_pk_mul_f32 v[184:185], v[228:229], v[184:185]
	v_pk_mul_f32 v[186:187], v[230:231], v[186:187]
	v_pk_mul_f32 v[190:191], v[132:133], v[190:191]
	v_pk_mul_f32 v[192:193], v[134:135], v[192:193]
	v_pk_add_f32 v[176:177], v[176:177], v[184:185]
	v_pk_add_f32 v[178:179], v[178:179], v[186:187]
	v_pk_add_f32 v[180:181], v[180:181], v[190:191]
	v_pk_add_f32 v[182:183], v[182:183], v[192:193]
	v_cndmask_b32_e64 v212, v212, v176, s[54:55]
	v_cndmask_b32_e64 v213, v213, v177, s[54:55]
	v_cndmask_b32_e64 v214, v214, v178, s[54:55]
	v_cndmask_b32_e64 v215, v215, v179, s[54:55]
	v_cndmask_b32_e64 v216, v216, v180, s[54:55]
	v_cndmask_b32_e64 v217, v217, v181, s[54:55]
	v_cndmask_b32_e64 v218, v218, v182, s[54:55]
	v_cndmask_b32_e64 v219, v219, v183, s[54:55]
	v_cvt_pk_bf16_f32 v228, v212, v213
	v_cvt_pk_bf16_f32 v229, v214, v215
	v_cvt_pk_bf16_f32 v230, v216, v217
	v_cvt_pk_bf16_f32 v231, v218, v219
	v_lshl_add_u64 v[132:133], s[14:15], 1, v[140:141]
	global_store_dwordx4 v[132:133], v[228:231], off

; __device__ __forceinline__ u32x4 pack8(const float (&v)[8]) { u32x4 w; w.x = pk2(v[0], v[1]); w.y = pk2(v[2], v[3]); w.z = pk2(v[4], v[5]); w.w = pk2(v[6], v[7]); return w; }
;     __device__ __forceinline__ bool operator()(Acc& acc, const Unit& u, int wr, int wc, int fr, int fq, const LAS float* rstab) const {
;     ...
;                 if (rope) {
;                     const float sgn = (fq == 0) ? -1.f : 1.f;
; #pragma unroll
;                     for (int ai = 0; ai < 2; ++ai)
; #pragma unroll
;                         for (int m = 0; m < 4; ++m) {
;                             const float rs = rsp[ai * HALF + m * 16] * scale;
;                             const int pos = (rowb + ai * HALF + m * 16) & (SEQ - 1);
;                             const f32x4 c0 = gld<f32x4>(ropec + pos * 8), c1 = gld<f32x4>(ropec + pos * 8 + 4);
;                             const f32x4 s0 = gld<f32x4>(ropes + pos * 8), s1 = gld<f32x4>(ropes + pos * 8 + 4);
;                             float v[8];
; #pragma unroll
;                             for (int e = 0; e < 4; ++e) { v[e] = acc[ai][bj][m][0][e] * rs; v[4 + e] = acc[ai][bj][m][1][e] * rs; }
; #pragma unroll
;                             for (int e = 0; e < 8; ++e) {
;                                 const float p = __shfl_xor(v[e], 16);
;                                 const float cs = e < 4 ? c0[e & 3] : c1[e & 3], sn = e < 4 ? s0[e & 3] : s1[e & 3];
;                                 const float r = v[e] * cs + sgn * p * sn;
;                                 v[e] = (fq < 2) ? r : v[e];
;                             }
;                             gst<u32x4>(p0 + (ai * HALF + m * 16) * pitch, pack8(v));
;                             asm volatile("" ::: "memory");
;                         }
.LBB0_450:
	s_andn2_b64 vcc, exec, s[58:59]
	s_cbranch_vccnz .LBB0_452
	v_and_b32_e32 v132, 64, v198
	v_xor_b32_e32 v0, 16, v198
	v_add_u32_e32 v132, 64, v132
	v_cmp_lt_i32_e32 vcc, v0, v132
	s_lshl_b32 s26, s61, 5
	s_mov_b32 s19, s27
	s_mov_b32 s17, s27
	s_mov_b32 s15, s27
	s_mov_b32 s13, s27
	v_cndmask_b32_e32 v0, v198, v0, vcc
	v_lshlrev_b32_e32 v0, 2, v0
	ds_read_b32 v188, v154
	v_lshlrev_b32_e32 v159, 5, v2
	v_and_b32_e32 v159, 0xf9e0, v159
	global_load_dwordx4 v[164:167], v159, s[20:21] offset:16
	global_load_dwordx4 v[160:163], v159, s[20:21]
	global_load_dwordx4 v[172:175], v159, s[22:23] offset:16
	global_load_dwordx4 v[168:171], v159, s[22:23]
	s_waitcnt lgkmcnt(0)
	v_mul_f32_e32 v188, s9, v188
	v_pk_mul_f32 v[212:213], v[128:129], v[188:189] op_sel_hi:[1,0]
	v_pk_mul_f32 v[214:215], v[130:131], v[188:189] op_sel_hi:[1,0]
	v_pk_mul_f32 v[216:217], v[124:125], v[188:189] op_sel_hi:[1,0]
	v_pk_mul_f32 v[218:219], v[126:127], v[188:189] op_sel_hi:[1,0]
	ds_bpermute_b32 v228, v0, v212
	ds_bpermute_b32 v229, v0, v213
	ds_bpermute_b32 v230, v0, v214
	ds_bpermute_b32 v231, v0, v215
	ds_bpermute_b32 v132, v0, v216
	ds_bpermute_b32 v133, v0, v217
	ds_bpermute_b32 v134, v0, v218
	ds_bpermute_b32 v135, v0, v219
	ds_read_b32 v189, v154 offset:64
	v_or_b32_e32 v136, 0x200, v159
	global_load_dwordx4 v[180:183], v136, s[20:21] offset:16
	global_load_dwordx4 v[176:179], v136, s[20:21]
	global_load_dwordx4 v[190:193], v136, s[22:23] offset:16
	global_load_dwordx4 v[184:187], v136, s[22:23]
	s_waitcnt lgkmcnt(1)
	s_waitcnt vmcnt(4)
	v_cndmask_b32_e64 v228, v228, -v228, s[56:57]
	v_cndmask_b32_e64 v229, v229, -v229, s[56:57]
	v_cndmask_b32_e64 v230, v230, -v230, s[56:57]
	v_cndmask_b32_e64 v231, v231, -v231, s[56:57]
	v_cndmask_b32_e64 v132, v132, -v132, s[56:57]
	v_cndmask_b32_e64 v133, v133, -v133, s[56:57]
	v_cndmask_b32_e64 v134, v134, -v134, s[56:57]
	v_cndmask_b32_e64 v135, v135, -v135, s[56:57]
	v_pk_mul_f32 v[160:161], v[212:213], v[160:161]
	v_pk_mul_f32 v[162:163], v[214:215], v[162:163]
	v_pk_mul_f32 v[164:165], v[216:217], v[164:165]
	v_pk_mul_f32 v[166:167], v[218:219], v[166:167]
	v_pk_mul_f32 v[168:169], v[228:229], v[168:169]
	v_pk_mul_f32 v[170:171], v[230:231], v[170:171]
	v_pk_mul_f32 v[172:173], v[132:133], v[172:173]
	v_pk_mul_f32 v[174:175], v[134:135], v[174:175]
	v_pk_add_f32 v[160:161], v[160:161], v[168:169]
	v_pk_add_f32 v[162:163], v[162:163], v[170:171]
	v_pk_add_f32 v[164:165], v[164:165], v[172:173]
	v_pk_add_f32 v[166:167], v[166:167], v[174:175]
	v_cndmask_b32_e64 v212, v212, v160, s[54:55]
	v_cndmask_b32_e64 v213, v213, v161, s[54:55]
	v_cndmask_b32_e64 v214, v214, v162, s[54:55]
	v_cndmask_b32_e64 v215, v215, v163, s[54:55]
	v_cndmask_b32_e64 v216, v216, v164, s[54:55]
	v_cndmask_b32_e64 v217, v217, v165, s[54:55]
	v_cndmask_b32_e64 v218, v218, v166, s[54:55]
	v_cndmask_b32_e64 v219, v219, v167, s[54:55]
	v_cvt_pk_bf16_f32 v228, v212, v213
	v_cvt_pk_bf16_f32 v229, v214, v215
	v_cvt_pk_bf16_f32 v230, v216, v217
	v_cvt_pk_bf16_f32 v231, v218, v219
	global_store_dwordx4 v[142:143], v[228:231], off
	s_waitcnt lgkmcnt(0)
	v_mul_f32_e32 v189, s9, v189
	v_pk_mul_f32 v[212:213], v[116:117], v[188:189] op_sel:[0,1]
	v_pk_mul_f32 v[214:215], v[118:119], v[188:189] op_sel:[0,1]
	v_pk_mul_f32 v[216:217], v[108:109], v[188:189] op_sel:[0,1]
	v_pk_mul_f32 v[218:219], v[110:111], v[188:189] op_sel:[0,1]
	ds_bpermute_b32 v228, v0, v212
	ds_bpermute_b32 v229, v0, v213
	ds_bpermute_b32 v230, v0, v214
	ds_bpermute_b32 v231, v0, v215
	ds_bpermute_b32 v132, v0, v216
	ds_bpermute_b32 v133, v0, v217
	ds_bpermute_b32 v134, v0, v218
	ds_bpermute_b32 v135, v0, v219
	ds_read_b32 v188, v154 offset:128
	v_or_b32_e32 v136, 0x400, v159
	global_load_dwordx4 v[164:167], v136, s[20:21] offset:16
	global_load_dwordx4 v[160:163], v136, s[20:21]
	global_load_dwordx4 v[172:175], v136, s[22:23] offset:16
	global_load_dwordx4 v[168:171], v136, s[22:23]
	s_waitcnt lgkmcnt(1)
	s_waitcnt vmcnt(5)
	v_cndmask_b32_e64 v228, v228, -v228, s[56:57]
	v_cndmask_b32_e64 v229, v229, -v229, s[56:57]
	v_cndmask_b32_e64 v230, v230, -v230, s[56:57]
	v_cndmask_b32_e64 v231, v231, -v231, s[56:57]
	v_cndmask_b32_e64 v132, v132, -v132, s[56:57]
	v_cndmask_b32_e64 v133, v133, -v133, s[56:57]
	v_cndmask_b32_e64 v134, v134, -v134, s[56:57]
	v_cndmask_b32_e64 v135, v135, -v135, s[56:57]
	v_pk_mul_f32 v[176:177], v[212:213], v[176:177]
	v_pk_mul_f32 v[178:179], v[214:215], v[178:179]
	v_pk_mul_f32 v[180:181], v[216:217], v[180:181]
	v_pk_mul_f32 v[182:183], v[218:219], v[182:183]
	v_pk_mul_f32 v[184:185], v[228:229], v[184:185]
	v_pk_mul_f32 v[186:187], v[230:231], v[186:187]
	v_pk_mul_f32 v[190:191], v[132:133], v[190:191]
	v_pk_mul_f32 v[192:193], v[134:135], v[192:193]
	v_pk_add_f32 v[176:177], v[176:177], v[184:185]
	v_pk_add_f32 v[178:179], v[178:179], v[186:187]
	v_pk_add_f32 v[180:181], v[180:181], v[190:191]
	v_pk_add_f32 v[182:183], v[182:183], v[192:193]
	v_cndmask_b32_e64 v212, v212, v176, s[54:55]
	v_cndmask_b32_e64 v213, v213, v177, s[54:55]
	v_cndmask_b32_e64 v214, v214, v178, s[54:55]
	v_cndmask_b32_e64 v215, v215, v179, s[54:55]
	v_cndmask_b32_e64 v216, v216, v180, s[54:55]
	v_cndmask_b32_e64 v217, v217, v181, s[54:55]
	v_cndmask_b32_e64 v218, v218, v182, s[54:55]
	v_cndmask_b32_e64 v219, v219, v183, s[54:55]
	v_cvt_pk_bf16_f32 v228, v212, v213
	v_cvt_pk_bf16_f32 v229, v214, v215
	v_cvt_pk_bf16_f32 v230, v216, v217
	v_cvt_pk_bf16_f32 v231, v218, v219
	v_lshl_add_u64 v[132:133], v[142:143], 0, s[26:27]
	global_store_dwordx4 v[132:133], v[228:231], off
	s_waitcnt lgkmcnt(0)
; __device__ __forceinline__ u32x4 pack8(const float (&v)[8]) { u32x4 w; w.x = pk2(v[0], v[1]); w.y = pk2(v[2], v[3]); w.z = pk2(v[4], v[5]); w.w = pk2(v[6], v[7]); return w; }
;     __device__ __forceinline__ bool operator()(Acc& acc, const Unit& u, int wr, int wc, int fr, int fq, const LAS float* rstab) const {
;     ...
;                 if (rope) {
;                     const float sgn = (fq == 0) ? -1.f : 1.f;
; #pragma unroll
;                     for (int ai = 0; ai < 2; ++ai)
; #pragma unroll
;                         for (int m = 0; m < 4; ++m) {
;                             const float rs = rsp[ai * HALF + m * 16] * scale;
;                             const int pos = (rowb + ai * HALF + m * 16) & (SEQ - 1);
;                             const f32x4 c0 = gld<f32x4>(ropec + pos * 8), c1 = gld<f32x4>(ropec + pos * 8 + 4);
;                             const f32x4 s0 = gld<f32x4>(ropes + pos * 8), s1 = gld<f32x4>(ropes + pos * 8 + 4);
;                             float v[8];
; #pragma unroll
;                             for (int e = 0; e < 4; ++e) { v[e] = acc[ai][bj][m][0][e] * rs; v[4 + e] = acc[ai][bj][m][1][e] * rs; }
; #pragma unroll
;                             for (int e = 0; e < 8; ++e) {
;                                 const float p = __shfl_xor(v[e], 16);
;                                 const float cs = e < 4 ? c0[e & 3] : c1[e & 3], sn = e < 4 ? s0[e & 3] : s1[e & 3];
;                                 const float r = v[e] * cs + sgn * p * sn;
;                                 v[e] = (fq < 2) ? r : v[e];
;                             }
;                             gst<u32x4>(p0 + (ai * HALF + m * 16) * pitch, pack8(v));
;                             asm volatile("" ::: "memory");
;                         }
	v_mul_f32_e32 v188, s9, v188
	v_pk_mul_f32 v[212:213], v[92:93], v[188:189] op_sel_hi:[1,0]
	v_pk_mul_f32 v[214:215], v[94:95], v[188:189] op_sel_hi:[1,0]
	v_pk_mul_f32 v[216:217], v[80:81], v[188:189] op_sel_hi:[1,0]
	v_pk_mul_f32 v[218:219], v[82:83], v[188:189] op_sel_hi:[1,0]
	ds_bpermute_b32 v228, v0, v212
	ds_bpermute_b32 v229, v0, v213
	ds_bpermute_b32 v230, v0, v214
	ds_bpermute_b32 v231, v0, v215
	ds_bpermute_b32 v132, v0, v216
	ds_bpermute_b32 v133, v0, v217
	ds_bpermute_b32 v134, v0, v218
	ds_bpermute_b32 v135, v0, v219
	ds_read_b32 v189, v154 offset:192
	v_or_b32_e32 v136, 0x600, v159
	global_load_dwordx4 v[180:183], v136, s[20:21] offset:16
	global_load_dwordx4 v[176:179], v136, s[20:21]
	global_load_dwordx4 v[190:193], v136, s[22:23] offset:16
	global_load_dwordx4 v[184:187], v136, s[22:23]
	s_waitcnt lgkmcnt(1)
	s_waitcnt vmcnt(5)
	v_cndmask_b32_e64 v228, v228, -v228, s[56:57]
	v_cndmask_b32_e64 v229, v229, -v229, s[56:57]
	v_cndmask_b32_e64 v230, v230, -v230, s[56:57]
	v_cndmask_b32_e64 v231, v231, -v231, s[56:57]
	v_cndmask_b32_e64 v132, v132, -v132, s[56:57]
	v_cndmask_b32_e64 v133, v133, -v133, s[56:57]
	v_cndmask_b32_e64 v134, v134, -v134, s[56:57]
	v_cndmask_b32_e64 v135, v135, -v135, s[56:57]
	v_pk_mul_f32 v[160:161], v[212:213], v[160:161]
	v_pk_mul_f32 v[162:163], v[214:215], v[162:163]
	v_pk_mul_f32 v[164:165], v[216:217], v[164:165]
	v_pk_mul_f32 v[166:167], v[218:219], v[166:167]
	v_pk_mul_f32 v[168:169], v[228:229], v[168:169]
	v_pk_mul_f32 v[170:171], v[230:231], v[170:171]
	v_pk_mul_f32 v[172:173], v[132:133], v[172:173]
	v_pk_mul_f32 v[174:175], v[134:135], v[174:175]
	v_pk_add_f32 v[160:161], v[160:161], v[168:169]
	v_pk_add_f32 v[162:163], v[162:163], v[170:171]
	v_pk_add_f32 v[164:165], v[164:165], v[172:173]
	v_pk_add_f32 v[166:167], v[166:167], v[174:175]
	v_cndmask_b32_e64 v212, v212, v160, s[54:55]
	v_cndmask_b32_e64 v213, v213, v161, s[54:55]
	v_cndmask_b32_e64 v214, v214, v162, s[54:55]
	v_cndmask_b32_e64 v215, v215, v163, s[54:55]
	v_cndmask_b32_e64 v216, v216, v164, s[54:55]
	v_cndmask_b32_e64 v217, v217, v165, s[54:55]
	v_cndmask_b32_e64 v218, v218, v166, s[54:55]
	v_cndmask_b32_e64 v219, v219, v167, s[54:55]
	v_cvt_pk_bf16_f32 v228, v212, v213
	v_cvt_pk_bf16_f32 v229, v214, v215
	v_cvt_pk_bf16_f32 v230, v216, v217
	v_cvt_pk_bf16_f32 v231, v218, v219
	v_lshl_add_u64 v[132:133], s[26:27], 1, v[142:143]
	global_store_dwordx4 v[132:133], v[228:231], off
	s_lshl_b32 s26, s61, 8
	s_waitcnt lgkmcnt(0)
	v_mul_f32_e32 v189, s9, v189
	v_pk_mul_f32 v[212:213], v[64:65], v[188:189] op_sel:[0,1]
	v_pk_mul_f32 v[214:215], v[66:67], v[188:189] op_sel:[0,1]
	v_pk_mul_f32 v[216:217], v[48:49], v[188:189] op_sel:[0,1]
	v_pk_mul_f32 v[218:219], v[50:51], v[188:189] op_sel:[0,1]
	ds_bpermute_b32 v228, v0, v212
	ds_bpermute_b32 v229, v0, v213
	ds_bpermute_b32 v230, v0, v214
	ds_bpermute_b32 v231, v0, v215
	ds_bpermute_b32 v132, v0, v216
	ds_bpermute_b32 v133, v0, v217
	ds_bpermute_b32 v134, v0, v218
	ds_bpermute_b32 v135, v0, v219
	ds_read_b32 v188, v154 offset:512
	v_mov_b32_e32 v159, 0x400
	v_lshl_add_u32 v159, v2, 3, v159
	v_and_b32_e32 v159, 0x3e78, v159
	v_lshlrev_b32_e32 v159, 2, v159
	global_load_dwordx4 v[164:167], v159, s[20:21] offset:16
	global_load_dwordx4 v[160:163], v159, s[20:21]
	global_load_dwordx4 v[172:175], v159, s[22:23] offset:16
	global_load_dwordx4 v[168:171], v159, s[22:23]
	s_waitcnt lgkmcnt(1)
	s_waitcnt vmcnt(5)
	v_cndmask_b32_e64 v228, v228, -v228, s[56:57]
	v_cndmask_b32_e64 v229, v229, -v229, s[56:57]
	v_cndmask_b32_e64 v230, v230, -v230, s[56:57]
	v_cndmask_b32_e64 v231, v231, -v231, s[56:57]
	v_cndmask_b32_e64 v132, v132, -v132, s[56:57]
	v_cndmask_b32_e64 v133, v133, -v133, s[56:57]
	v_cndmask_b32_e64 v134, v134, -v134, s[56:57]
	v_cndmask_b32_e64 v135, v135, -v135, s[56:57]
	v_pk_mul_f32 v[176:177], v[212:213], v[176:177]
	v_pk_mul_f32 v[178:179], v[214:215], v[178:179]
	v_pk_mul_f32 v[180:181], v[216:217], v[180:181]
	v_pk_mul_f32 v[182:183], v[218:219], v[182:183]
	v_pk_mul_f32 v[184:185], v[228:229], v[184:185]
	v_pk_mul_f32 v[186:187], v[230:231], v[186:187]
	v_pk_mul_f32 v[190:191], v[132:133], v[190:191]
	v_pk_mul_f32 v[192:193], v[134:135], v[192:193]
	v_pk_add_f32 v[176:177], v[176:177], v[184:185]
	v_pk_add_f32 v[178:179], v[178:179], v[186:187]
	v_pk_add_f32 v[180:181], v[180:181], v[190:191]
	v_pk_add_f32 v[182:183], v[182:183], v[192:193]
	v_cndmask_b32_e64 v212, v212, v176, s[54:55]
	v_cndmask_b32_e64 v213, v213, v177, s[54:55]
	v_cndmask_b32_e64 v214, v214, v178, s[54:55]
	v_cndmask_b32_e64 v215, v215, v179, s[54:55]
	v_cndmask_b32_e64 v216, v216, v180, s[54:55]
	v_cndmask_b32_e64 v217, v217, v181, s[54:55]
	v_cndmask_b32_e64 v218, v218, v182, s[54:55]
	v_cndmask_b32_e64 v219, v219, v183, s[54:55]
	v_cvt_pk_bf16_f32 v228, v212, v213
	v_cvt_pk_bf16_f32 v229, v214, v215
	v_cvt_pk_bf16_f32 v230, v216, v217
	v_cvt_pk_bf16_f32 v231, v218, v219
	v_lshl_add_u64 v[132:133], s[18:19], 1, v[142:143]
	global_store_dwordx4 v[132:133], v[228:231], off
	s_waitcnt lgkmcnt(0)
	v_mul_f32_e32 v188, s9, v188
	v_pk_mul_f32 v[212:213], v[96:97], v[188:189] op_sel_hi:[1,0]
	v_pk_mul_f32 v[214:215], v[98:99], v[188:189] op_sel_hi:[1,0]
	v_pk_mul_f32 v[216:217], v[104:105], v[188:189] op_sel_hi:[1,0]
	v_pk_mul_f32 v[218:219], v[106:107], v[188:189] op_sel_hi:[1,0]
	ds_bpermute_b32 v228, v0, v212
	ds_bpermute_b32 v229, v0, v213
	ds_bpermute_b32 v230, v0, v214
	ds_bpermute_b32 v231, v0, v215
	ds_bpermute_b32 v132, v0, v216
	ds_bpermute_b32 v133, v0, v217
	ds_bpermute_b32 v134, v0, v218
	ds_bpermute_b32 v135, v0, v219
	ds_read_b32 v189, v154 offset:576
	v_or_b32_e32 v136, 0x200, v159
	global_load_dwordx4 v[180:183], v136, s[20:21] offset:16
	global_load_dwordx4 v[176:179], v136, s[20:21]
	global_load_dwordx4 v[190:193], v136, s[22:23] offset:16
	global_load_dwordx4 v[184:187], v136, s[22:23]
	s_waitcnt lgkmcnt(1)
; __device__ __forceinline__ u32x4 pack8(const float (&v)[8]) { u32x4 w; w.x = pk2(v[0], v[1]); w.y = pk2(v[2], v[3]); w.z = pk2(v[4], v[5]); w.w = pk2(v[6], v[7]); return w; }
;     __device__ __forceinline__ bool operator()(Acc& acc, const Unit& u, int wr, int wc, int fr, int fq, const LAS float* rstab) const {
;     ...
;                 if (rope) {
;                     const float sgn = (fq == 0) ? -1.f : 1.f;
; #pragma unroll
;                     for (int ai = 0; ai < 2; ++ai)
; #pragma unroll
;                         for (int m = 0; m < 4; ++m) {
;                             const float rs = rsp[ai * HALF + m * 16] * scale;
;                             const int pos = (rowb + ai * HALF + m * 16) & (SEQ - 1);
;                             const f32x4 c0 = gld<f32x4>(ropec + pos * 8), c1 = gld<f32x4>(ropec + pos * 8 + 4);
;                             const f32x4 s0 = gld<f32x4>(ropes + pos * 8), s1 = gld<f32x4>(ropes + pos * 8 + 4);
;                             float v[8];
; #pragma unroll
;                             for (int e = 0; e < 4; ++e) { v[e] = acc[ai][bj][m][0][e] * rs; v[4 + e] = acc[ai][bj][m][1][e] * rs; }
; #pragma unroll
;                             for (int e = 0; e < 8; ++e) {
;                                 const float p = __shfl_xor(v[e], 16);
;                                 const float cs = e < 4 ? c0[e & 3] : c1[e & 3], sn = e < 4 ? s0[e & 3] : s1[e & 3];
;                                 const float r = v[e] * cs + sgn * p * sn;
;                                 v[e] = (fq < 2) ? r : v[e];
;                             }
;                             gst<u32x4>(p0 + (ai * HALF + m * 16) * pitch, pack8(v));
;                             asm volatile("" ::: "memory");
;                         }
	s_waitcnt vmcnt(5)
	v_cndmask_b32_e64 v228, v228, -v228, s[56:57]
	v_cndmask_b32_e64 v229, v229, -v229, s[56:57]
	v_cndmask_b32_e64 v230, v230, -v230, s[56:57]
	v_cndmask_b32_e64 v231, v231, -v231, s[56:57]
	v_cndmask_b32_e64 v132, v132, -v132, s[56:57]
	v_cndmask_b32_e64 v133, v133, -v133, s[56:57]
	v_cndmask_b32_e64 v134, v134, -v134, s[56:57]
	v_cndmask_b32_e64 v135, v135, -v135, s[56:57]
	v_pk_mul_f32 v[160:161], v[212:213], v[160:161]
	v_pk_mul_f32 v[162:163], v[214:215], v[162:163]
	v_pk_mul_f32 v[164:165], v[216:217], v[164:165]
	v_pk_mul_f32 v[166:167], v[218:219], v[166:167]
	v_pk_mul_f32 v[168:169], v[228:229], v[168:169]
	v_pk_mul_f32 v[170:171], v[230:231], v[170:171]
	v_pk_mul_f32 v[172:173], v[132:133], v[172:173]
	v_pk_mul_f32 v[174:175], v[134:135], v[174:175]
	v_pk_add_f32 v[160:161], v[160:161], v[168:169]
	v_pk_add_f32 v[162:163], v[162:163], v[170:171]
	v_pk_add_f32 v[164:165], v[164:165], v[172:173]
	v_pk_add_f32 v[166:167], v[166:167], v[174:175]
	v_cndmask_b32_e64 v212, v212, v160, s[54:55]
	v_cndmask_b32_e64 v213, v213, v161, s[54:55]
	v_cndmask_b32_e64 v214, v214, v162, s[54:55]
	v_cndmask_b32_e64 v215, v215, v163, s[54:55]
	v_cndmask_b32_e64 v216, v216, v164, s[54:55]
	v_cndmask_b32_e64 v217, v217, v165, s[54:55]
	v_cndmask_b32_e64 v218, v218, v166, s[54:55]
	v_cndmask_b32_e64 v219, v219, v167, s[54:55]
	v_cvt_pk_bf16_f32 v228, v212, v213
	v_cvt_pk_bf16_f32 v229, v214, v215
	v_cvt_pk_bf16_f32 v230, v216, v217
	v_cvt_pk_bf16_f32 v231, v218, v219
	v_lshl_add_u64 v[132:133], v[142:143], 0, s[26:27]
	global_store_dwordx4 v[132:133], v[228:231], off
	s_waitcnt lgkmcnt(0)
	v_mul_f32_e32 v189, s9, v189
	v_pk_mul_f32 v[212:213], v[84:85], v[188:189] op_sel:[0,1]
	v_pk_mul_f32 v[214:215], v[86:87], v[188:189] op_sel:[0,1]
	v_pk_mul_f32 v[216:217], v[76:77], v[188:189] op_sel:[0,1]
	v_pk_mul_f32 v[218:219], v[78:79], v[188:189] op_sel:[0,1]
	ds_bpermute_b32 v228, v0, v212
	ds_bpermute_b32 v229, v0, v213
	ds_bpermute_b32 v230, v0, v214
	ds_bpermute_b32 v231, v0, v215
	ds_bpermute_b32 v132, v0, v216
	ds_bpermute_b32 v133, v0, v217
	ds_bpermute_b32 v134, v0, v218
	ds_bpermute_b32 v135, v0, v219
	ds_read_b32 v188, v154 offset:640
	v_or_b32_e32 v136, 0x400, v159
	global_load_dwordx4 v[164:167], v136, s[20:21] offset:16
	global_load_dwordx4 v[160:163], v136, s[20:21]
	global_load_dwordx4 v[172:175], v136, s[22:23] offset:16
	global_load_dwordx4 v[168:171], v136, s[22:23]
	s_waitcnt lgkmcnt(1)
	s_waitcnt vmcnt(5)
	v_cndmask_b32_e64 v228, v228, -v228, s[56:57]
	v_cndmask_b32_e64 v229, v229, -v229, s[56:57]
	v_cndmask_b32_e64 v230, v230, -v230, s[56:57]
	v_cndmask_b32_e64 v231, v231, -v231, s[56:57]
	v_cndmask_b32_e64 v132, v132, -v132, s[56:57]
	v_cndmask_b32_e64 v133, v133, -v133, s[56:57]
	v_cndmask_b32_e64 v134, v134, -v134, s[56:57]
	v_cndmask_b32_e64 v135, v135, -v135, s[56:57]
	v_pk_mul_f32 v[176:177], v[212:213], v[176:177]
	v_pk_mul_f32 v[178:179], v[214:215], v[178:179]
	v_pk_mul_f32 v[180:181], v[216:217], v[180:181]
	v_pk_mul_f32 v[182:183], v[218:219], v[182:183]
	v_pk_mul_f32 v[184:185], v[228:229], v[184:185]
	v_pk_mul_f32 v[186:187], v[230:231], v[186:187]
	v_pk_mul_f32 v[190:191], v[132:133], v[190:191]
	v_pk_mul_f32 v[192:193], v[134:135], v[192:193]
	v_pk_add_f32 v[176:177], v[176:177], v[184:185]
	v_pk_add_f32 v[178:179], v[178:179], v[186:187]
	v_pk_add_f32 v[180:181], v[180:181], v[190:191]
	v_pk_add_f32 v[182:183], v[182:183], v[192:193]
	v_cndmask_b32_e64 v212, v212, v176, s[54:55]
	v_cndmask_b32_e64 v213, v213, v177, s[54:55]
	v_cndmask_b32_e64 v214, v214, v178, s[54:55]
	v_cndmask_b32_e64 v215, v215, v179, s[54:55]
	v_cndmask_b32_e64 v216, v216, v180, s[54:55]
	v_cndmask_b32_e64 v217, v217, v181, s[54:55]
	v_cndmask_b32_e64 v218, v218, v182, s[54:55]
	v_cndmask_b32_e64 v219, v219, v183, s[54:55]
	v_cvt_pk_bf16_f32 v228, v212, v213
	v_cvt_pk_bf16_f32 v229, v214, v215
	v_cvt_pk_bf16_f32 v230, v216, v217
	v_cvt_pk_bf16_f32 v231, v218, v219
	v_lshl_add_u64 v[132:133], s[16:17], 1, v[142:143]
	global_store_dwordx4 v[132:133], v[228:231], off
	s_waitcnt lgkmcnt(0)
; __device__ __forceinline__ u32x4 pack8(const float (&v)[8]) { u32x4 w; w.x = pk2(v[0], v[1]); w.y = pk2(v[2], v[3]); w.z = pk2(v[4], v[5]); w.w = pk2(v[6], v[7]); return w; }
;     __device__ __forceinline__ bool operator()(Acc& acc, const Unit& u, int wr, int wc, int fr, int fq, const LAS float* rstab) const {
;     ...
;                 if (rope) {
;                     const float sgn = (fq == 0) ? -1.f : 1.f;
; #pragma unroll
;                     for (int ai = 0; ai < 2; ++ai)
; #pragma unroll
;                         for (int m = 0; m < 4; ++m) {
;                             const float rs = rsp[ai * HALF + m * 16] * scale;
;                             const int pos = (rowb + ai * HALF + m * 16) & (SEQ - 1);
;                             const f32x4 c0 = gld<f32x4>(ropec + pos * 8), c1 = gld<f32x4>(ropec + pos * 8 + 4);
;                             const f32x4 s0 = gld<f32x4>(ropes + pos * 8), s1 = gld<f32x4>(ropes + pos * 8 + 4);
;                             float v[8];
; #pragma unroll
;                             for (int e = 0; e < 4; ++e) { v[e] = acc[ai][bj][m][0][e] * rs; v[4 + e] = acc[ai][bj][m][1][e] * rs; }
; #pragma unroll
;                             for (int e = 0; e < 8; ++e) {
;                                 const float p = __shfl_xor(v[e], 16);
;                                 const float cs = e < 4 ? c0[e & 3] : c1[e & 3], sn = e < 4 ? s0[e & 3] : s1[e & 3];
;                                 const float r = v[e] * cs + sgn * p * sn;
;                                 v[e] = (fq < 2) ? r : v[e];
;                             }
;                             gst<u32x4>(p0 + (ai * HALF + m * 16) * pitch, pack8(v));
;                             asm volatile("" ::: "memory");
;                         }
	v_mul_f32_e32 v188, s9, v188
	v_pk_mul_f32 v[212:213], v[52:53], v[188:189] op_sel_hi:[1,0]
	v_pk_mul_f32 v[214:215], v[54:55], v[188:189] op_sel_hi:[1,0]
	v_pk_mul_f32 v[216:217], v[44:45], v[188:189] op_sel_hi:[1,0]
	v_pk_mul_f32 v[218:219], v[46:47], v[188:189] op_sel_hi:[1,0]
	ds_bpermute_b32 v228, v0, v212
	ds_bpermute_b32 v229, v0, v213
	ds_bpermute_b32 v230, v0, v214
	ds_bpermute_b32 v231, v0, v215
	ds_bpermute_b32 v132, v0, v216
	ds_bpermute_b32 v133, v0, v217
	ds_bpermute_b32 v134, v0, v218
	ds_bpermute_b32 v135, v0, v219
	ds_read_b32 v189, v154 offset:704
	v_or_b32_e32 v136, 0x600, v159
	global_load_dwordx4 v[180:183], v136, s[20:21] offset:16
	global_load_dwordx4 v[176:179], v136, s[20:21]
	global_load_dwordx4 v[190:193], v136, s[22:23] offset:16
	global_load_dwordx4 v[184:187], v136, s[22:23]
	s_waitcnt lgkmcnt(1)
	s_waitcnt vmcnt(5)
	v_cndmask_b32_e64 v228, v228, -v228, s[56:57]
	v_cndmask_b32_e64 v229, v229, -v229, s[56:57]
	v_cndmask_b32_e64 v230, v230, -v230, s[56:57]
	v_cndmask_b32_e64 v231, v231, -v231, s[56:57]
	v_cndmask_b32_e64 v132, v132, -v132, s[56:57]
	v_cndmask_b32_e64 v133, v133, -v133, s[56:57]
	v_cndmask_b32_e64 v134, v134, -v134, s[56:57]
	v_cndmask_b32_e64 v135, v135, -v135, s[56:57]
	v_pk_mul_f32 v[160:161], v[212:213], v[160:161]
	v_pk_mul_f32 v[162:163], v[214:215], v[162:163]
	v_pk_mul_f32 v[164:165], v[216:217], v[164:165]
	v_pk_mul_f32 v[166:167], v[218:219], v[166:167]
	v_pk_mul_f32 v[168:169], v[228:229], v[168:169]
	v_pk_mul_f32 v[170:171], v[230:231], v[170:171]
	v_pk_mul_f32 v[172:173], v[132:133], v[172:173]
	v_pk_mul_f32 v[174:175], v[134:135], v[174:175]
	v_pk_add_f32 v[160:161], v[160:161], v[168:169]
	v_pk_add_f32 v[162:163], v[162:163], v[170:171]
	v_pk_add_f32 v[164:165], v[164:165], v[172:173]
	v_pk_add_f32 v[166:167], v[166:167], v[174:175]
	v_cndmask_b32_e64 v212, v212, v160, s[54:55]
	v_cndmask_b32_e64 v213, v213, v161, s[54:55]
	v_cndmask_b32_e64 v214, v214, v162, s[54:55]
	v_cndmask_b32_e64 v215, v215, v163, s[54:55]
	v_cndmask_b32_e64 v216, v216, v164, s[54:55]
	v_cndmask_b32_e64 v217, v217, v165, s[54:55]
	v_cndmask_b32_e64 v218, v218, v166, s[54:55]
	v_cndmask_b32_e64 v219, v219, v167, s[54:55]
	v_cvt_pk_bf16_f32 v228, v212, v213
	v_cvt_pk_bf16_f32 v229, v214, v215
	v_cvt_pk_bf16_f32 v230, v216, v217
	v_cvt_pk_bf16_f32 v231, v218, v219
	v_lshl_add_u64 v[132:133], s[14:15], 1, v[142:143]
	global_store_dwordx4 v[132:133], v[228:231], off
	s_waitcnt lgkmcnt(0)
	v_mul_f32_e32 v189, s9, v189
	v_pk_mul_f32 v[212:213], v[24:25], v[188:189] op_sel:[0,1]
	v_pk_mul_f32 v[214:215], v[26:27], v[188:189] op_sel:[0,1]
	v_pk_mul_f32 v[216:217], v[20:21], v[188:189] op_sel:[0,1]
	v_pk_mul_f32 v[218:219], v[22:23], v[188:189] op_sel:[0,1]
	ds_bpermute_b32 v228, v0, v212
	ds_bpermute_b32 v229, v0, v213
	ds_bpermute_b32 v230, v0, v214
	ds_bpermute_b32 v231, v0, v215
	ds_bpermute_b32 v132, v0, v216
	ds_bpermute_b32 v133, v0, v217
	ds_bpermute_b32 v134, v0, v218
	ds_bpermute_b32 v135, v0, v219
	s_waitcnt lgkmcnt(0)
	s_waitcnt vmcnt(1)
	v_cndmask_b32_e64 v228, v228, -v228, s[56:57]
	v_cndmask_b32_e64 v229, v229, -v229, s[56:57]
	v_cndmask_b32_e64 v230, v230, -v230, s[56:57]
	v_cndmask_b32_e64 v231, v231, -v231, s[56:57]
	v_cndmask_b32_e64 v132, v132, -v132, s[56:57]
	v_cndmask_b32_e64 v133, v133, -v133, s[56:57]
	v_cndmask_b32_e64 v134, v134, -v134, s[56:57]
	v_cndmask_b32_e64 v135, v135, -v135, s[56:57]
	v_pk_mul_f32 v[176:177], v[212:213], v[176:177]
	v_pk_mul_f32 v[178:179], v[214:215], v[178:179]
	v_pk_mul_f32 v[180:181], v[216:217], v[180:181]
	v_pk_mul_f32 v[182:183], v[218:219], v[182:183]
	v_pk_mul_f32 v[184:185], v[228:229], v[184:185]
	v_pk_mul_f32 v[186:187], v[230:231], v[186:187]
	v_pk_mul_f32 v[190:191], v[132:133], v[190:191]
	v_pk_mul_f32 v[192:193], v[134:135], v[192:193]
	v_pk_add_f32 v[176:177], v[176:177], v[184:185]
	v_pk_add_f32 v[178:179], v[178:179], v[186:187]
	v_pk_add_f32 v[180:181], v[180:181], v[190:191]
	v_pk_add_f32 v[182:183], v[182:183], v[192:193]
	v_cndmask_b32_e64 v212, v212, v176, s[54:55]
	v_cndmask_b32_e64 v213, v213, v177, s[54:55]
	v_cndmask_b32_e64 v214, v214, v178, s[54:55]
	v_cndmask_b32_e64 v215, v215, v179, s[54:55]
	v_cndmask_b32_e64 v216, v216, v180, s[54:55]
	v_cndmask_b32_e64 v217, v217, v181, s[54:55]
	v_cndmask_b32_e64 v218, v218, v182, s[54:55]
	v_cndmask_b32_e64 v219, v219, v183, s[54:55]
	v_cvt_pk_bf16_f32 v228, v212, v213
	v_cvt_pk_bf16_f32 v229, v214, v215
	v_cvt_pk_bf16_f32 v230, v216, v217
	v_cvt_pk_bf16_f32 v231, v218, v219
	v_lshl_add_u64 v[132:133], s[12:13], 1, v[142:143]
	global_store_dwordx4 v[132:133], v[228:231], off

; #define LAS __attribute__((address_space(3)))
; __device__ __forceinline__ void unpack8(const u32x4 w, float (&v)[8]) { v[0] = bflo(w.x); v[1] = bfhi(w.x); v[2] = bflo(w.y); v[3] = bfhi(w.y); v[4] = bflo(w.z); v[5] = bfhi(w.z); v[6] = bflo(w.w); v[7] = bfhi(w.w); }
; __device__ __forceinline__ u32x4 pack8(const float (&v)[8]) { u32x4 w; w.x = pk2(v[0], v[1]); w.y = pk2(v[2], v[3]); w.z = pk2(v[4], v[5]); w.w = pk2(v[6], v[7]); return w; }
; __device__ __forceinline__ float sigmoidf_(float x) { return __builtin_amdgcn_rcpf(1.0f + __builtin_amdgcn_exp2f(-LOG2E * x)); }
;     __device__ __forceinline__ bool operator()(Acc& acc, const Unit& u, int wr, int wc, int fr, int fq, const LAS float*) const {
;         const size_t o0 = (size_t)(u.pm * BM + wr * 64 + fr) * 512 + u.pn * BM + wc * 32 + 8 * fq; const bf16_t* yp = YS + o0; bf16_t* zp = Z + o0;
;         u32x4 yv[2][4][2];
; #pragma unroll
;         for (int ai = 0; ai < 2; ++ai)
; #pragma unroll
;             for (int m = 0; m < 4; ++m)
; #pragma unroll
;                 for (int bj = 0; bj < 2; ++bj) yv[ai][m][bj] = gld<u32x4>(yp + (ai * HALF + m * 16) * 512 + bj * HALF);
; #pragma unroll
;         for (int ai = 0; ai < 2; ++ai) {
; #pragma unroll
;             for (int m = 0; m < 4; ++m)
; #pragma unroll
;                 for (int bj = 0; bj < 2; ++bj) {
;                     float y[8]; unpack8(yv[ai][m][bj], y);
;                     float v[8];
; #pragma unroll
;                     for (int e = 0; e < 4; ++e) { v[e] = y[e] * sigmoidf_(acc[ai][bj][m][0][e]); v[4 + e] = y[4 + e] * sigmoidf_(acc[ai][bj][m][1][e]); }
;                     gst<u32x4>(zp + (ai * HALF + m * 16) * 512 + bj * HALF, pack8(v));
;                 }
;             asm volatile("" ::: "memory");
;         }
;         return true;
;     }
.LBB0_705:
	v_mov_b32_e32 v34, v1
	s_lshl_b32 s8, s21, 8
	v_mbcnt_lo_u32_b32 v34, -1, v34
	v_readlane_b32 s9, v250, 1
	v_mbcnt_hi_u32_b32 v36, -1, v34
	s_add_i32 s8, s8, s9
	v_and_or_b32 v34, v36, 15, s8
	v_ashrrev_i32_e32 v35, 31, v34
	s_lshl_b32 s8, s20, 8
	v_lshlrev_b64 v[34:35], 9, v[34:35]
	s_ashr_i32 s9, s8, 31
	v_lshl_add_u64 v[34:35], v[34:35], 0, s[8:9]
	v_lshrrev_b32_e32 v36, 1, v36
	v_and_or_b32 v34, v36, 24, v34
	v_readlane_b32 s8, v254, 32
	v_mul_f32_e32 v178, 0xbfb8aa3b, v178
	v_mul_f32_e32 v179, 0xbfb8aa3b, v179
	v_or_b32_e32 v34, s8, v34
	v_lshlrev_b64 v[194:195], 1, v[34:35]
	v_lshl_add_u64 v[34:35], s[22:23], 0, v[194:195]
	global_load_dwordx4 v[190:193], v[34:35], off
	global_load_dwordx4 v[186:189], v[34:35], off offset:256
	s_movk_i32 s8, 0x4000
	v_add_co_u32_e32 v36, vcc, s8, v34
	v_exp_f32_e32 v178, v178
	s_nop 0
	v_addc_co_u32_e32 v37, vcc, 0, v35, vcc
	global_load_dwordx4 v[182:185], v[36:37], off
	global_load_dwordx4 v[174:177], v[36:37], off offset:256
	v_mul_f32_e32 v170, 0xbfb8aa3b, v170
	v_exp_f32_e32 v179, v179
	v_mul_f32_e32 v171, 0xbfb8aa3b, v171
	v_mul_f32_e32 v180, 0xbfb8aa3b, v180
	v_mul_f32_e32 v181, 0xbfb8aa3b, v181
	v_exp_f32_e32 v170, v170
	v_exp_f32_e32 v171, v171
	v_exp_f32_e32 v180, v180
	v_exp_f32_e32 v181, v181
	v_mul_f32_e32 v162, 0xbfb8aa3b, v162
	v_mul_f32_e32 v163, 0xbfb8aa3b, v163
	v_exp_f32_e32 v162, v162
	v_mul_f32_e32 v158, 0xbfb8aa3b, v158
	v_exp_f32_e32 v163, v163
	v_mul_f32_e32 v159, 0xbfb8aa3b, v159
	v_pk_add_f32 v[178:179], v[178:179], 1.0 op_sel_hi:[1,0]
	v_exp_f32_e32 v158, v158
	v_exp_f32_e32 v159, v159
	v_rcp_f32_e32 v178, v178
	v_pk_add_f32 v[170:171], v[170:171], 1.0 op_sel_hi:[1,0]
	v_rcp_f32_e32 v179, v179
	v_pk_add_f32 v[180:181], v[180:181], 1.0 op_sel_hi:[1,0]
	v_readlane_b32 s14, v254, 55
	v_rcp_f32_e32 v170, v170
	v_rcp_f32_e32 v171, v171
	v_rcp_f32_e32 v180, v180
	v_rcp_f32_e32 v181, v181
	v_readlane_b32 s15, v254, 56
	v_pk_add_f32 v[162:163], v[162:163], 1.0 op_sel_hi:[1,0]
	v_lshl_add_u64 v[212:213], s[14:15], 0, v[194:195]
	v_rcp_f32_e32 v162, v162
	v_pk_add_f32 v[158:159], v[158:159], 1.0 op_sel_hi:[1,0]
	v_rcp_f32_e32 v163, v163
	v_rcp_f32_e32 v158, v158
	v_rcp_f32_e32 v159, v159
	s_mov_b32 s9, 0x8000
	v_add_co_u32_e32 v36, vcc, s9, v34
	v_mul_f32_e32 v172, 0xbfb8aa3b, v172
	s_nop 0
	v_addc_co_u32_e32 v37, vcc, 0, v35, vcc
	global_load_dwordx4 v[166:169], v[36:37], off
	global_load_dwordx4 v[154:157], v[36:37], off offset:256
	v_mul_f32_e32 v173, 0xbfb8aa3b, v173
	v_exp_f32_e32 v172, v172
	v_exp_f32_e32 v173, v173
	s_mov_b32 s10, 0xc000
	v_add_co_u32_e32 v36, vcc, s10, v34
	v_mul_f32_e32 v150, 0xbfb8aa3b, v150
	s_nop 0
	v_addc_co_u32_e32 v37, vcc, 0, v35, vcc
	v_mul_f32_e32 v151, 0xbfb8aa3b, v151
	global_load_dwordx4 v[142:145], v[36:37], off
	global_load_dwordx4 v[130:133], v[36:37], off offset:256
	v_add_co_u32_e32 v36, vcc, s79, v34
	v_pk_add_f32 v[172:173], v[172:173], 1.0 op_sel_hi:[1,0]
	v_exp_f32_e32 v150, v150
	v_mul_f32_e32 v146, 0xbfb8aa3b, v146
	v_exp_f32_e32 v151, v151
	v_mul_f32_e32 v147, 0xbfb8aa3b, v147
	v_addc_co_u32_e32 v37, vcc, 0, v35, vcc
	s_mov_b32 s11, 0x24000
	v_rcp_f32_e32 v172, v172
	v_rcp_f32_e32 v173, v173
	s_waitcnt vmcnt(7)
	v_lshlrev_b32_e32 v194, 16, v190
	v_and_b32_e32 v195, 0xffff0000, v190
	v_pk_mul_f32 v[178:179], v[178:179], v[194:195]
	v_lshlrev_b32_e32 v194, 16, v192
	v_and_b32_e32 v195, 0xffff0000, v192
	v_lshlrev_b32_e32 v190, 16, v191
	v_and_b32_e32 v191, 0xffff0000, v191
	v_pk_mul_f32 v[170:171], v[170:171], v[194:195]
	v_pk_mul_f32 v[180:181], v[180:181], v[190:191]
	v_cvt_pk_bf16_f32 v178, v178, v179
	v_cvt_pk_bf16_f32 v179, v180, v181
	v_cvt_pk_bf16_f32 v180, v170, v171
	s_waitcnt vmcnt(6)
	v_lshlrev_b32_e32 v170, 16, v186
	v_and_b32_e32 v171, 0xffff0000, v186
	v_pk_mul_f32 v[162:163], v[162:163], v[170:171]
	v_lshlrev_b32_e32 v170, 16, v188
	v_and_b32_e32 v171, 0xffff0000, v188
	v_pk_mul_f32 v[170:171], v[158:159], v[170:171]
	v_mul_f32_e32 v159, 0xbfb8aa3b, v160
	v_exp_f32_e32 v159, v159
	v_mul_f32_e32 v158, 0xbfb8aa3b, v164
	v_exp_f32_e32 v158, v158
	v_lshlrev_b32_e32 v164, 16, v187
	v_add_f32_e32 v159, 1.0, v159
	v_rcp_f32_e32 v160, v159
	v_mul_f32_e32 v159, 0xbfb8aa3b, v165
	v_exp_f32_e32 v159, v159
	v_add_f32_e32 v158, 1.0, v158
	v_rcp_f32_e32 v158, v158
	v_and_b32_e32 v165, 0xffff0000, v187
	v_add_f32_e32 v159, 1.0, v159
	v_rcp_f32_e32 v159, v159
	v_exp_f32_e32 v146, v146
	v_exp_f32_e32 v147, v147
	global_load_dwordx4 v[118:121], v[36:37], off
	global_load_dwordx4 v[106:109], v[36:37], off offset:256
	v_pk_mul_f32 v[164:165], v[158:159], v[164:165]
	v_mul_f32_e32 v158, 0xbfb8aa3b, v161
	v_exp_f32_e32 v158, v158
	v_add_co_u32_e32 v36, vcc, s11, v34
	s_mov_b32 s12, 0x28000
	v_add_f32_e32 v158, 1.0, v158
	v_rcp_f32_e32 v161, v158
	v_addc_co_u32_e32 v37, vcc, 0, v35, vcc
	global_load_dwordx4 v[94:97], v[36:37], off
	global_load_dwordx4 v[82:85], v[36:37], off offset:256
	v_add_co_u32_e32 v36, vcc, s12, v34
	v_lshlrev_b32_e32 v190, 16, v193
	v_and_b32_e32 v191, 0xffff0000, v193
	v_pk_add_f32 v[150:151], v[150:151], 1.0 op_sel_hi:[1,0]
	v_addc_co_u32_e32 v37, vcc, 0, v35, vcc
	s_mov_b32 s13, 0x2c000
	v_pk_mul_f32 v[172:173], v[172:173], v[190:191]
	v_lshlrev_b32_e32 v158, 16, v189
	v_and_b32_e32 v159, 0xffff0000, v189
	v_rcp_f32_e32 v150, v150
	v_pk_add_f32 v[146:147], v[146:147], 1.0 op_sel_hi:[1,0]
	v_rcp_f32_e32 v151, v151
	v_add_co_u32_e32 v34, vcc, s13, v34
	v_cvt_pk_bf16_f32 v181, v172, v173
	v_pk_mul_f32 v[172:173], v[160:161], v[158:159]
	v_rcp_f32_e32 v146, v146
	v_rcp_f32_e32 v147, v147
	v_addc_co_u32_e32 v35, vcc, 0, v35, vcc
	v_cvt_pk_bf16_f32 v158, v162, v163
	v_cvt_pk_bf16_f32 v159, v164, v165
	v_cvt_pk_bf16_f32 v160, v170, v171
	v_cvt_pk_bf16_f32 v161, v172, v173
	global_load_dwordx4 v[70:73], v[36:37], off
	global_load_dwordx4 v[58:61], v[36:37], off offset:256
	global_load_dwordx4 v[46:49], v[34:35], off
	s_nop 0
	global_load_dwordx4 v[34:37], v[34:35], off offset:256
	v_mul_f32_e32 v138, 0xbfb8aa3b, v138
	global_store_dwordx4 v[212:213], v[158:161], off offset:256
	v_mul_f32_e32 v139, 0xbfb8aa3b, v139
	v_exp_f32_e32 v138, v138
	s_waitcnt vmcnt(14)
; #define LAS __attribute__((address_space(3)))
; __device__ __forceinline__ void unpack8(const u32x4 w, float (&v)[8]) { v[0] = bflo(w.x); v[1] = bfhi(w.x); v[2] = bflo(w.y); v[3] = bfhi(w.y); v[4] = bflo(w.z); v[5] = bfhi(w.z); v[6] = bflo(w.w); v[7] = bfhi(w.w); }
; __device__ __forceinline__ u32x4 pack8(const float (&v)[8]) { u32x4 w; w.x = pk2(v[0], v[1]); w.y = pk2(v[2], v[3]); w.z = pk2(v[4], v[5]); w.w = pk2(v[6], v[7]); return w; }
; __device__ __forceinline__ float sigmoidf_(float x) { return __builtin_amdgcn_rcpf(1.0f + __builtin_amdgcn_exp2f(-LOG2E * x)); }
;     __device__ __forceinline__ bool operator()(Acc& acc, const Unit& u, int wr, int wc, int fr, int fq, const LAS float*) const {
;         const size_t o0 = (size_t)(u.pm * BM + wr * 64 + fr) * 512 + u.pn * BM + wc * 32 + 8 * fq; const bf16_t* yp = YS + o0; bf16_t* zp = Z + o0;
;         u32x4 yv[2][4][2];
; #pragma unroll
;         for (int ai = 0; ai < 2; ++ai)
; #pragma unroll
;             for (int m = 0; m < 4; ++m)
; #pragma unroll
;                 for (int bj = 0; bj < 2; ++bj) yv[ai][m][bj] = gld<u32x4>(yp + (ai * HALF + m * 16) * 512 + bj * HALF);
; #pragma unroll
;         for (int ai = 0; ai < 2; ++ai) {
; #pragma unroll
;             for (int m = 0; m < 4; ++m)
; #pragma unroll
;                 for (int bj = 0; bj < 2; ++bj) {
;                     float y[8]; unpack8(yv[ai][m][bj], y);
;                     float v[8];
; #pragma unroll
;                     for (int e = 0; e < 4; ++e) { v[e] = y[e] * sigmoidf_(acc[ai][bj][m][0][e]); v[4 + e] = y[4 + e] * sigmoidf_(acc[ai][bj][m][1][e]); }
;                     gst<u32x4>(zp + (ai * HALF + m * 16) * 512 + bj * HALF, pack8(v));
;                 }
;             asm volatile("" ::: "memory");
;         }
;         return true;
;     }
	v_lshlrev_b32_e32 v158, 16, v182
	v_and_b32_e32 v159, 0xffff0000, v182
	v_pk_mul_f32 v[150:151], v[150:151], v[158:159]
	v_lshlrev_b32_e32 v158, 16, v184
	v_and_b32_e32 v159, 0xffff0000, v184
	v_pk_mul_f32 v[158:159], v[146:147], v[158:159]
	v_mul_f32_e32 v147, 0xbfb8aa3b, v148
	v_exp_f32_e32 v147, v147
	v_mul_f32_e32 v146, 0xbfb8aa3b, v152
	v_exp_f32_e32 v146, v146
	v_lshlrev_b32_e32 v152, 16, v183
	v_add_f32_e32 v147, 1.0, v147
	v_rcp_f32_e32 v148, v147
	v_mul_f32_e32 v147, 0xbfb8aa3b, v153
	v_exp_f32_e32 v147, v147
	v_add_f32_e32 v146, 1.0, v146
	v_rcp_f32_e32 v146, v146
	v_and_b32_e32 v153, 0xffff0000, v183
	v_add_f32_e32 v147, 1.0, v147
	v_rcp_f32_e32 v147, v147
	v_mul_f32_e32 v134, 0xbfb8aa3b, v134
	v_exp_f32_e32 v139, v139
	v_mul_f32_e32 v135, 0xbfb8aa3b, v135
	v_pk_mul_f32 v[152:153], v[146:147], v[152:153]
	v_mul_f32_e32 v146, 0xbfb8aa3b, v149
	v_exp_f32_e32 v146, v146
	v_exp_f32_e32 v134, v134
	v_exp_f32_e32 v135, v135
	v_pk_add_f32 v[138:139], v[138:139], 1.0 op_sel_hi:[1,0]
	v_add_f32_e32 v146, 1.0, v146
	v_rcp_f32_e32 v149, v146
	v_lshlrev_b32_e32 v146, 16, v185
	v_and_b32_e32 v147, 0xffff0000, v185
	v_rcp_f32_e32 v138, v138
	v_pk_add_f32 v[134:135], v[134:135], 1.0 op_sel_hi:[1,0]
	v_rcp_f32_e32 v139, v139
	v_pk_mul_f32 v[160:161], v[148:149], v[146:147]
	v_cvt_pk_bf16_f32 v146, v150, v151
	v_add_co_u32_e32 v150, vcc, s8, v212
	v_rcp_f32_e32 v134, v134
	v_rcp_f32_e32 v135, v135
	v_cvt_pk_bf16_f32 v147, v152, v153
	v_cvt_pk_bf16_f32 v148, v158, v159
	v_cvt_pk_bf16_f32 v149, v160, v161
	v_addc_co_u32_e32 v151, vcc, 0, v213, vcc
	global_store_dwordx4 v[150:151], v[146:149], off
	v_mul_f32_e32 v126, 0xbfb8aa3b, v126
	v_mul_f32_e32 v127, 0xbfb8aa3b, v127
	s_waitcnt vmcnt(14)
	v_lshlrev_b32_e32 v146, 16, v174
	v_and_b32_e32 v147, 0xffff0000, v174
	v_pk_mul_f32 v[138:139], v[138:139], v[146:147]
	v_lshlrev_b32_e32 v146, 16, v176
	v_and_b32_e32 v147, 0xffff0000, v176
	v_pk_mul_f32 v[146:147], v[134:135], v[146:147]
	v_mul_f32_e32 v135, 0xbfb8aa3b, v136
	v_exp_f32_e32 v135, v135
	v_mul_f32_e32 v134, 0xbfb8aa3b, v140
	v_exp_f32_e32 v134, v134
	v_lshlrev_b32_e32 v140, 16, v175
	v_add_f32_e32 v135, 1.0, v135
	v_rcp_f32_e32 v136, v135
	v_mul_f32_e32 v135, 0xbfb8aa3b, v141
	v_exp_f32_e32 v135, v135
	v_add_f32_e32 v134, 1.0, v134
	v_rcp_f32_e32 v134, v134
	v_and_b32_e32 v141, 0xffff0000, v175
	v_add_f32_e32 v135, 1.0, v135
	v_rcp_f32_e32 v135, v135
	v_exp_f32_e32 v126, v126
	v_mul_f32_e32 v122, 0xbfb8aa3b, v122
	v_exp_f32_e32 v127, v127
	v_pk_mul_f32 v[140:141], v[134:135], v[140:141]
	v_mul_f32_e32 v134, 0xbfb8aa3b, v137
	v_exp_f32_e32 v134, v134
	v_mul_f32_e32 v123, 0xbfb8aa3b, v123
	v_exp_f32_e32 v122, v122
	v_exp_f32_e32 v123, v123
	v_add_f32_e32 v134, 1.0, v134
	v_rcp_f32_e32 v137, v134
	v_pk_add_f32 v[126:127], v[126:127], 1.0 op_sel_hi:[1,0]
	v_lshlrev_b32_e32 v134, 16, v177
	v_and_b32_e32 v135, 0xffff0000, v177
	v_rcp_f32_e32 v126, v126
	v_pk_add_f32 v[122:123], v[122:123], 1.0 op_sel_hi:[1,0]
	v_rcp_f32_e32 v127, v127
	v_pk_mul_f32 v[148:149], v[136:137], v[134:135]
	v_rcp_f32_e32 v122, v122
	v_rcp_f32_e32 v123, v123
	v_cvt_pk_bf16_f32 v134, v138, v139
	v_cvt_pk_bf16_f32 v135, v140, v141
	v_cvt_pk_bf16_f32 v136, v146, v147
	v_cvt_pk_bf16_f32 v137, v148, v149
	global_store_dwordx4 v[150:151], v[134:137], off offset:256
	v_mul_f32_e32 v114, 0xbfb8aa3b, v114
	v_mul_f32_e32 v115, 0xbfb8aa3b, v115
	s_waitcnt vmcnt(14)
	v_lshlrev_b32_e32 v134, 16, v166
	v_and_b32_e32 v135, 0xffff0000, v166
	v_pk_mul_f32 v[126:127], v[126:127], v[134:135]
	v_lshlrev_b32_e32 v134, 16, v168
	v_and_b32_e32 v135, 0xffff0000, v168
	v_pk_mul_f32 v[134:135], v[122:123], v[134:135]
	v_mul_f32_e32 v123, 0xbfb8aa3b, v124
	v_exp_f32_e32 v123, v123
	v_mul_f32_e32 v122, 0xbfb8aa3b, v128
	v_exp_f32_e32 v122, v122
	v_lshlrev_b32_e32 v128, 16, v167
	v_add_f32_e32 v123, 1.0, v123
	v_rcp_f32_e32 v124, v123
	v_mul_f32_e32 v123, 0xbfb8aa3b, v129
	v_exp_f32_e32 v123, v123
	v_add_f32_e32 v122, 1.0, v122
	v_rcp_f32_e32 v122, v122
	v_and_b32_e32 v129, 0xffff0000, v167
	v_add_f32_e32 v123, 1.0, v123
	v_rcp_f32_e32 v123, v123
	v_exp_f32_e32 v114, v114
	v_mul_f32_e32 v110, 0xbfb8aa3b, v110
	v_exp_f32_e32 v115, v115
	v_pk_mul_f32 v[128:129], v[122:123], v[128:129]
	v_mul_f32_e32 v122, 0xbfb8aa3b, v125
	v_exp_f32_e32 v122, v122
	v_mul_f32_e32 v111, 0xbfb8aa3b, v111
	v_exp_f32_e32 v110, v110
	v_exp_f32_e32 v111, v111
	v_add_f32_e32 v122, 1.0, v122
	v_rcp_f32_e32 v125, v122
	v_pk_add_f32 v[114:115], v[114:115], 1.0 op_sel_hi:[1,0]
	v_lshlrev_b32_e32 v122, 16, v169
	v_and_b32_e32 v123, 0xffff0000, v169
	v_rcp_f32_e32 v114, v114
	v_pk_add_f32 v[110:111], v[110:111], 1.0 op_sel_hi:[1,0]
	v_rcp_f32_e32 v115, v115
	v_pk_mul_f32 v[136:137], v[124:125], v[122:123]
	v_cvt_pk_bf16_f32 v122, v126, v127
	v_add_co_u32_e32 v126, vcc, s9, v212
	v_rcp_f32_e32 v110, v110
	v_rcp_f32_e32 v111, v111
	v_cvt_pk_bf16_f32 v123, v128, v129
	v_cvt_pk_bf16_f32 v124, v134, v135
	v_cvt_pk_bf16_f32 v125, v136, v137
	v_addc_co_u32_e32 v127, vcc, 0, v213, vcc
	global_store_dwordx4 v[126:127], v[122:125], off
	v_mul_f32_e32 v102, 0xbfb8aa3b, v102
	v_mul_f32_e32 v103, 0xbfb8aa3b, v103
	s_waitcnt vmcnt(14)
; #define LAS __attribute__((address_space(3)))
; __device__ __forceinline__ void unpack8(const u32x4 w, float (&v)[8]) { v[0] = bflo(w.x); v[1] = bfhi(w.x); v[2] = bflo(w.y); v[3] = bfhi(w.y); v[4] = bflo(w.z); v[5] = bfhi(w.z); v[6] = bflo(w.w); v[7] = bfhi(w.w); }
; __device__ __forceinline__ u32x4 pack8(const float (&v)[8]) { u32x4 w; w.x = pk2(v[0], v[1]); w.y = pk2(v[2], v[3]); w.z = pk2(v[4], v[5]); w.w = pk2(v[6], v[7]); return w; }
; __device__ __forceinline__ float sigmoidf_(float x) { return __builtin_amdgcn_rcpf(1.0f + __builtin_amdgcn_exp2f(-LOG2E * x)); }
;     __device__ __forceinline__ bool operator()(Acc& acc, const Unit& u, int wr, int wc, int fr, int fq, const LAS float*) const {
;         const size_t o0 = (size_t)(u.pm * BM + wr * 64 + fr) * 512 + u.pn * BM + wc * 32 + 8 * fq; const bf16_t* yp = YS + o0; bf16_t* zp = Z + o0;
;         u32x4 yv[2][4][2];
; #pragma unroll
;         for (int ai = 0; ai < 2; ++ai)
; #pragma unroll
;             for (int m = 0; m < 4; ++m)
; #pragma unroll
;                 for (int bj = 0; bj < 2; ++bj) yv[ai][m][bj] = gld<u32x4>(yp + (ai * HALF + m * 16) * 512 + bj * HALF);
; #pragma unroll
;         for (int ai = 0; ai < 2; ++ai) {
; #pragma unroll
;             for (int m = 0; m < 4; ++m)
; #pragma unroll
;                 for (int bj = 0; bj < 2; ++bj) {
;                     float y[8]; unpack8(yv[ai][m][bj], y);
;                     float v[8];
; #pragma unroll
;                     for (int e = 0; e < 4; ++e) { v[e] = y[e] * sigmoidf_(acc[ai][bj][m][0][e]); v[4 + e] = y[4 + e] * sigmoidf_(acc[ai][bj][m][1][e]); }
;                     gst<u32x4>(zp + (ai * HALF + m * 16) * 512 + bj * HALF, pack8(v));
;                 }
;             asm volatile("" ::: "memory");
;         }
;         return true;
;     }
	v_lshlrev_b32_e32 v122, 16, v154
	v_and_b32_e32 v123, 0xffff0000, v154
	v_pk_mul_f32 v[114:115], v[114:115], v[122:123]
	v_lshlrev_b32_e32 v122, 16, v156
	v_and_b32_e32 v123, 0xffff0000, v156
	v_pk_mul_f32 v[122:123], v[110:111], v[122:123]
	v_mul_f32_e32 v111, 0xbfb8aa3b, v112
	v_exp_f32_e32 v111, v111
	v_mul_f32_e32 v110, 0xbfb8aa3b, v116
	v_exp_f32_e32 v110, v110
	v_lshlrev_b32_e32 v116, 16, v155
	v_add_f32_e32 v111, 1.0, v111
	v_rcp_f32_e32 v112, v111
	v_mul_f32_e32 v111, 0xbfb8aa3b, v117
	v_exp_f32_e32 v111, v111
	v_add_f32_e32 v110, 1.0, v110
	v_rcp_f32_e32 v110, v110
	v_and_b32_e32 v117, 0xffff0000, v155
	v_add_f32_e32 v111, 1.0, v111
	v_rcp_f32_e32 v111, v111
	v_exp_f32_e32 v102, v102
	v_mul_f32_e32 v98, 0xbfb8aa3b, v98
	v_exp_f32_e32 v103, v103
	v_pk_mul_f32 v[116:117], v[110:111], v[116:117]
	v_mul_f32_e32 v110, 0xbfb8aa3b, v113
	v_exp_f32_e32 v110, v110
	v_mul_f32_e32 v99, 0xbfb8aa3b, v99
	v_exp_f32_e32 v98, v98
	v_exp_f32_e32 v99, v99
	v_add_f32_e32 v110, 1.0, v110
	v_rcp_f32_e32 v113, v110
	v_pk_add_f32 v[102:103], v[102:103], 1.0 op_sel_hi:[1,0]
	v_lshlrev_b32_e32 v110, 16, v157
	v_and_b32_e32 v111, 0xffff0000, v157
	v_rcp_f32_e32 v102, v102
	v_pk_add_f32 v[98:99], v[98:99], 1.0 op_sel_hi:[1,0]
	v_rcp_f32_e32 v103, v103
	v_pk_mul_f32 v[124:125], v[112:113], v[110:111]
	v_rcp_f32_e32 v98, v98
	v_rcp_f32_e32 v99, v99
	v_cvt_pk_bf16_f32 v110, v114, v115
	v_cvt_pk_bf16_f32 v111, v116, v117
	v_cvt_pk_bf16_f32 v112, v122, v123
	v_cvt_pk_bf16_f32 v113, v124, v125
	global_store_dwordx4 v[126:127], v[110:113], off offset:256
	v_mul_f32_e32 v90, 0xbfb8aa3b, v90
	v_mul_f32_e32 v91, 0xbfb8aa3b, v91
	s_waitcnt vmcnt(14)
	v_lshlrev_b32_e32 v110, 16, v142
	v_and_b32_e32 v111, 0xffff0000, v142
	v_pk_mul_f32 v[102:103], v[102:103], v[110:111]
	v_lshlrev_b32_e32 v110, 16, v144
	v_and_b32_e32 v111, 0xffff0000, v144
	v_pk_mul_f32 v[110:111], v[98:99], v[110:111]
	v_mul_f32_e32 v99, 0xbfb8aa3b, v100
	v_exp_f32_e32 v99, v99
	v_mul_f32_e32 v98, 0xbfb8aa3b, v104
	v_exp_f32_e32 v98, v98
	v_lshlrev_b32_e32 v104, 16, v143
	v_add_f32_e32 v99, 1.0, v99
	v_rcp_f32_e32 v100, v99
	v_mul_f32_e32 v99, 0xbfb8aa3b, v105
	v_exp_f32_e32 v99, v99
	v_add_f32_e32 v98, 1.0, v98
	v_rcp_f32_e32 v98, v98
	v_and_b32_e32 v105, 0xffff0000, v143
	v_add_f32_e32 v99, 1.0, v99
	v_rcp_f32_e32 v99, v99
	v_exp_f32_e32 v90, v90
	v_mul_f32_e32 v86, 0xbfb8aa3b, v86
	v_exp_f32_e32 v91, v91
	v_pk_mul_f32 v[104:105], v[98:99], v[104:105]
	v_mul_f32_e32 v98, 0xbfb8aa3b, v101
	v_exp_f32_e32 v98, v98
	v_mul_f32_e32 v87, 0xbfb8aa3b, v87
	v_exp_f32_e32 v86, v86
	v_exp_f32_e32 v87, v87
	v_add_f32_e32 v98, 1.0, v98
	v_rcp_f32_e32 v101, v98
	v_pk_add_f32 v[90:91], v[90:91], 1.0 op_sel_hi:[1,0]
	v_lshlrev_b32_e32 v98, 16, v145
	v_and_b32_e32 v99, 0xffff0000, v145
	v_rcp_f32_e32 v90, v90
	v_pk_add_f32 v[86:87], v[86:87], 1.0 op_sel_hi:[1,0]
	v_rcp_f32_e32 v91, v91
	v_pk_mul_f32 v[112:113], v[100:101], v[98:99]
	v_cvt_pk_bf16_f32 v98, v102, v103
	v_add_co_u32_e32 v102, vcc, s10, v212
	v_rcp_f32_e32 v86, v86
	v_rcp_f32_e32 v87, v87
	v_cvt_pk_bf16_f32 v99, v104, v105
	v_cvt_pk_bf16_f32 v100, v110, v111
	v_cvt_pk_bf16_f32 v101, v112, v113
	v_addc_co_u32_e32 v103, vcc, 0, v213, vcc
	global_store_dwordx4 v[102:103], v[98:101], off
	v_mul_f32_e32 v78, 0xbfb8aa3b, v78
	v_mul_f32_e32 v79, 0xbfb8aa3b, v79
	s_waitcnt vmcnt(14)
	v_lshlrev_b32_e32 v98, 16, v130
	v_and_b32_e32 v99, 0xffff0000, v130
	v_pk_mul_f32 v[90:91], v[90:91], v[98:99]
	v_lshlrev_b32_e32 v98, 16, v132
	v_and_b32_e32 v99, 0xffff0000, v132
	v_pk_mul_f32 v[98:99], v[86:87], v[98:99]
	v_mul_f32_e32 v87, 0xbfb8aa3b, v88
	v_exp_f32_e32 v87, v87
	v_mul_f32_e32 v86, 0xbfb8aa3b, v92
	v_exp_f32_e32 v86, v86
	v_lshlrev_b32_e32 v92, 16, v131
	v_add_f32_e32 v87, 1.0, v87
	v_rcp_f32_e32 v88, v87
	v_mul_f32_e32 v87, 0xbfb8aa3b, v93
	v_exp_f32_e32 v87, v87
	v_add_f32_e32 v86, 1.0, v86
	v_rcp_f32_e32 v86, v86
	v_and_b32_e32 v93, 0xffff0000, v131
	v_add_f32_e32 v87, 1.0, v87
	v_rcp_f32_e32 v87, v87
	v_exp_f32_e32 v78, v78
	v_mul_f32_e32 v74, 0xbfb8aa3b, v74
	v_exp_f32_e32 v79, v79
	v_pk_mul_f32 v[92:93], v[86:87], v[92:93]
	v_mul_f32_e32 v86, 0xbfb8aa3b, v89
	v_exp_f32_e32 v86, v86
	v_mul_f32_e32 v75, 0xbfb8aa3b, v75
	v_exp_f32_e32 v74, v74
	v_exp_f32_e32 v75, v75
	v_add_f32_e32 v86, 1.0, v86
	v_rcp_f32_e32 v89, v86
	v_pk_add_f32 v[78:79], v[78:79], 1.0 op_sel_hi:[1,0]
	v_lshlrev_b32_e32 v86, 16, v133
	v_and_b32_e32 v87, 0xffff0000, v133
	v_rcp_f32_e32 v78, v78
	v_pk_add_f32 v[74:75], v[74:75], 1.0 op_sel_hi:[1,0]
	v_rcp_f32_e32 v79, v79
	v_pk_mul_f32 v[100:101], v[88:89], v[86:87]
	v_rcp_f32_e32 v74, v74
	v_rcp_f32_e32 v75, v75
	v_cvt_pk_bf16_f32 v86, v90, v91
	v_cvt_pk_bf16_f32 v87, v92, v93
	v_cvt_pk_bf16_f32 v88, v98, v99
	v_cvt_pk_bf16_f32 v89, v100, v101
	global_store_dwordx4 v[102:103], v[86:89], off offset:256
	v_mul_f32_e32 v66, 0xbfb8aa3b, v66
	v_mul_f32_e32 v67, 0xbfb8aa3b, v67
	s_waitcnt vmcnt(14)
; #define LAS __attribute__((address_space(3)))
; __device__ __forceinline__ void unpack8(const u32x4 w, float (&v)[8]) { v[0] = bflo(w.x); v[1] = bfhi(w.x); v[2] = bflo(w.y); v[3] = bfhi(w.y); v[4] = bflo(w.z); v[5] = bfhi(w.z); v[6] = bflo(w.w); v[7] = bfhi(w.w); }
; __device__ __forceinline__ u32x4 pack8(const float (&v)[8]) { u32x4 w; w.x = pk2(v[0], v[1]); w.y = pk2(v[2], v[3]); w.z = pk2(v[4], v[5]); w.w = pk2(v[6], v[7]); return w; }
; __device__ __forceinline__ float sigmoidf_(float x) { return __builtin_amdgcn_rcpf(1.0f + __builtin_amdgcn_exp2f(-LOG2E * x)); }
;     __device__ __forceinline__ bool operator()(Acc& acc, const Unit& u, int wr, int wc, int fr, int fq, const LAS float*) const {
;         const size_t o0 = (size_t)(u.pm * BM + wr * 64 + fr) * 512 + u.pn * BM + wc * 32 + 8 * fq; const bf16_t* yp = YS + o0; bf16_t* zp = Z + o0;
;         u32x4 yv[2][4][2];
; #pragma unroll
;         for (int ai = 0; ai < 2; ++ai)
; #pragma unroll
;             for (int m = 0; m < 4; ++m)
; #pragma unroll
;                 for (int bj = 0; bj < 2; ++bj) yv[ai][m][bj] = gld<u32x4>(yp + (ai * HALF + m * 16) * 512 + bj * HALF);
; #pragma unroll
;         for (int ai = 0; ai < 2; ++ai) {
; #pragma unroll
;             for (int m = 0; m < 4; ++m)
; #pragma unroll
;                 for (int bj = 0; bj < 2; ++bj) {
;                     float y[8]; unpack8(yv[ai][m][bj], y);
;                     float v[8];
; #pragma unroll
;                     for (int e = 0; e < 4; ++e) { v[e] = y[e] * sigmoidf_(acc[ai][bj][m][0][e]); v[4 + e] = y[4 + e] * sigmoidf_(acc[ai][bj][m][1][e]); }
;                     gst<u32x4>(zp + (ai * HALF + m * 16) * 512 + bj * HALF, pack8(v));
;                 }
;             asm volatile("" ::: "memory");
;         }
;         return true;
;     }
	v_lshlrev_b32_e32 v86, 16, v118
	v_and_b32_e32 v87, 0xffff0000, v118
	v_pk_mul_f32 v[78:79], v[78:79], v[86:87]
	v_lshlrev_b32_e32 v86, 16, v120
	v_and_b32_e32 v87, 0xffff0000, v120
	v_pk_mul_f32 v[86:87], v[74:75], v[86:87]
	v_mul_f32_e32 v75, 0xbfb8aa3b, v76
	v_exp_f32_e32 v75, v75
	v_mul_f32_e32 v74, 0xbfb8aa3b, v80
	v_exp_f32_e32 v74, v74
	v_lshlrev_b32_e32 v80, 16, v119
	v_add_f32_e32 v75, 1.0, v75
	v_rcp_f32_e32 v76, v75
	v_mul_f32_e32 v75, 0xbfb8aa3b, v81
	v_exp_f32_e32 v75, v75
	v_add_f32_e32 v74, 1.0, v74
	v_rcp_f32_e32 v74, v74
	v_and_b32_e32 v81, 0xffff0000, v119
	v_add_f32_e32 v75, 1.0, v75
	v_rcp_f32_e32 v75, v75
	v_exp_f32_e32 v66, v66
	v_mul_f32_e32 v62, 0xbfb8aa3b, v62
	v_exp_f32_e32 v67, v67
	v_pk_mul_f32 v[80:81], v[74:75], v[80:81]
	v_mul_f32_e32 v74, 0xbfb8aa3b, v77
	v_exp_f32_e32 v74, v74
	v_mul_f32_e32 v63, 0xbfb8aa3b, v63
	v_exp_f32_e32 v62, v62
	v_exp_f32_e32 v63, v63
	v_add_f32_e32 v74, 1.0, v74
	v_rcp_f32_e32 v77, v74
	v_pk_add_f32 v[66:67], v[66:67], 1.0 op_sel_hi:[1,0]
	v_lshlrev_b32_e32 v74, 16, v121
	v_and_b32_e32 v75, 0xffff0000, v121
	v_rcp_f32_e32 v66, v66
	v_pk_add_f32 v[62:63], v[62:63], 1.0 op_sel_hi:[1,0]
	v_rcp_f32_e32 v67, v67
	v_pk_mul_f32 v[88:89], v[76:77], v[74:75]
	v_cvt_pk_bf16_f32 v74, v78, v79
	v_add_co_u32_e32 v78, vcc, s79, v212
	v_rcp_f32_e32 v62, v62
	v_rcp_f32_e32 v63, v63
	global_store_dwordx4 v[212:213], v[178:181], off
	v_cvt_pk_bf16_f32 v75, v80, v81
	v_cvt_pk_bf16_f32 v76, v86, v87
	v_cvt_pk_bf16_f32 v77, v88, v89
	v_addc_co_u32_e32 v79, vcc, 0, v213, vcc
	global_store_dwordx4 v[78:79], v[74:77], off
	v_mul_f32_e32 v54, 0xbfb8aa3b, v54
	v_mul_f32_e32 v55, 0xbfb8aa3b, v55
	s_waitcnt vmcnt(15)
	v_lshlrev_b32_e32 v74, 16, v106
	v_and_b32_e32 v75, 0xffff0000, v106
	v_pk_mul_f32 v[66:67], v[66:67], v[74:75]
	v_lshlrev_b32_e32 v74, 16, v108
	v_and_b32_e32 v75, 0xffff0000, v108
	v_pk_mul_f32 v[74:75], v[62:63], v[74:75]
	v_mul_f32_e32 v63, 0xbfb8aa3b, v64
	v_exp_f32_e32 v63, v63
	v_mul_f32_e32 v62, 0xbfb8aa3b, v68
	v_exp_f32_e32 v62, v62
	v_lshlrev_b32_e32 v68, 16, v107
	v_add_f32_e32 v63, 1.0, v63
	v_rcp_f32_e32 v64, v63
	v_mul_f32_e32 v63, 0xbfb8aa3b, v69
	v_exp_f32_e32 v63, v63
	v_add_f32_e32 v62, 1.0, v62
	v_rcp_f32_e32 v62, v62
	v_and_b32_e32 v69, 0xffff0000, v107
	v_add_f32_e32 v63, 1.0, v63
	v_rcp_f32_e32 v63, v63
	v_exp_f32_e32 v54, v54
	v_mul_f32_e32 v50, 0xbfb8aa3b, v50
	v_exp_f32_e32 v55, v55
	v_pk_mul_f32 v[68:69], v[62:63], v[68:69]
	v_mul_f32_e32 v62, 0xbfb8aa3b, v65
	v_exp_f32_e32 v62, v62
	v_mul_f32_e32 v51, 0xbfb8aa3b, v51
	v_exp_f32_e32 v50, v50
	v_exp_f32_e32 v51, v51
	v_add_f32_e32 v62, 1.0, v62
	v_rcp_f32_e32 v65, v62
	v_pk_add_f32 v[54:55], v[54:55], 1.0 op_sel_hi:[1,0]
	v_lshlrev_b32_e32 v62, 16, v109
	v_and_b32_e32 v63, 0xffff0000, v109
	v_rcp_f32_e32 v54, v54
	v_pk_add_f32 v[50:51], v[50:51], 1.0 op_sel_hi:[1,0]
	v_rcp_f32_e32 v55, v55
	v_pk_mul_f32 v[76:77], v[64:65], v[62:63]
	v_rcp_f32_e32 v50, v50
	v_rcp_f32_e32 v51, v51
	v_cvt_pk_bf16_f32 v62, v66, v67
	v_cvt_pk_bf16_f32 v63, v68, v69
	v_cvt_pk_bf16_f32 v64, v74, v75
	v_cvt_pk_bf16_f32 v65, v76, v77
	global_store_dwordx4 v[78:79], v[62:65], off offset:256
	v_mul_f32_e32 v42, 0xbfb8aa3b, v42
	v_mul_f32_e32 v43, 0xbfb8aa3b, v43
	s_waitcnt vmcnt(15)
	v_lshlrev_b32_e32 v62, 16, v94
	v_and_b32_e32 v63, 0xffff0000, v94
	v_pk_mul_f32 v[54:55], v[54:55], v[62:63]
	v_lshlrev_b32_e32 v62, 16, v96
	v_and_b32_e32 v63, 0xffff0000, v96
	v_pk_mul_f32 v[62:63], v[50:51], v[62:63]
	v_mul_f32_e32 v51, 0xbfb8aa3b, v52
	v_exp_f32_e32 v51, v51
	v_mul_f32_e32 v50, 0xbfb8aa3b, v56
	v_exp_f32_e32 v50, v50
	v_lshlrev_b32_e32 v56, 16, v95
	v_add_f32_e32 v51, 1.0, v51
	v_rcp_f32_e32 v52, v51
	v_mul_f32_e32 v51, 0xbfb8aa3b, v57
	v_exp_f32_e32 v51, v51
	v_add_f32_e32 v50, 1.0, v50
	v_rcp_f32_e32 v50, v50
	v_and_b32_e32 v57, 0xffff0000, v95
	v_add_f32_e32 v51, 1.0, v51
	v_rcp_f32_e32 v51, v51
	v_exp_f32_e32 v42, v42
	v_mul_f32_e32 v38, 0xbfb8aa3b, v38
	v_exp_f32_e32 v43, v43
	v_pk_mul_f32 v[56:57], v[50:51], v[56:57]
	v_mul_f32_e32 v50, 0xbfb8aa3b, v53
	v_exp_f32_e32 v50, v50
	v_mul_f32_e32 v39, 0xbfb8aa3b, v39
	v_exp_f32_e32 v38, v38
	v_exp_f32_e32 v39, v39
	v_add_f32_e32 v50, 1.0, v50
	v_rcp_f32_e32 v53, v50
	v_pk_add_f32 v[42:43], v[42:43], 1.0 op_sel_hi:[1,0]
	v_lshlrev_b32_e32 v50, 16, v97
	v_and_b32_e32 v51, 0xffff0000, v97
	v_rcp_f32_e32 v42, v42
	v_pk_add_f32 v[38:39], v[38:39], 1.0 op_sel_hi:[1,0]
	v_rcp_f32_e32 v43, v43
	v_pk_mul_f32 v[64:65], v[52:53], v[50:51]
	v_cvt_pk_bf16_f32 v50, v54, v55
	v_add_co_u32_e32 v54, vcc, s11, v212
	v_rcp_f32_e32 v38, v38
	v_rcp_f32_e32 v39, v39
	v_cvt_pk_bf16_f32 v51, v56, v57
	v_cvt_pk_bf16_f32 v52, v62, v63
	v_cvt_pk_bf16_f32 v53, v64, v65
	v_addc_co_u32_e32 v55, vcc, 0, v213, vcc
	global_store_dwordx4 v[54:55], v[50:53], off
	v_mul_f32_e32 v30, 0xbfb8aa3b, v30
	v_mul_f32_e32 v31, 0xbfb8aa3b, v31
	s_waitcnt vmcnt(15)
	v_lshlrev_b32_e32 v50, 16, v82
	v_and_b32_e32 v51, 0xffff0000, v82
	v_pk_mul_f32 v[42:43], v[42:43], v[50:51]
	v_lshlrev_b32_e32 v50, 16, v84
	v_and_b32_e32 v51, 0xffff0000, v84
	v_pk_mul_f32 v[50:51], v[38:39], v[50:51]
	v_mul_f32_e32 v39, 0xbfb8aa3b, v40
	v_exp_f32_e32 v39, v39
	v_mul_f32_e32 v38, 0xbfb8aa3b, v44
	v_exp_f32_e32 v38, v38
	v_lshlrev_b32_e32 v44, 16, v83
	v_add_f32_e32 v39, 1.0, v39
	v_rcp_f32_e32 v40, v39
	v_mul_f32_e32 v39, 0xbfb8aa3b, v45
	v_exp_f32_e32 v39, v39
	v_add_f32_e32 v38, 1.0, v38
	v_rcp_f32_e32 v38, v38
	v_and_b32_e32 v45, 0xffff0000, v83
	v_add_f32_e32 v39, 1.0, v39
	v_rcp_f32_e32 v39, v39
	v_exp_f32_e32 v30, v30
	v_mul_f32_e32 v26, 0xbfb8aa3b, v26
	v_exp_f32_e32 v31, v31
	v_pk_mul_f32 v[44:45], v[38:39], v[44:45]
	v_mul_f32_e32 v38, 0xbfb8aa3b, v41
	v_exp_f32_e32 v38, v38
	v_mul_f32_e32 v27, 0xbfb8aa3b, v27
	v_exp_f32_e32 v26, v26
	v_exp_f32_e32 v27, v27
	v_add_f32_e32 v38, 1.0, v38
	v_rcp_f32_e32 v41, v38
	v_pk_add_f32 v[30:31], v[30:31], 1.0 op_sel_hi:[1,0]
	v_lshlrev_b32_e32 v38, 16, v85
	v_and_b32_e32 v39, 0xffff0000, v85
	v_rcp_f32_e32 v30, v30
	v_pk_add_f32 v[26:27], v[26:27], 1.0 op_sel_hi:[1,0]
	v_rcp_f32_e32 v31, v31
	v_pk_mul_f32 v[52:53], v[40:41], v[38:39]
	v_rcp_f32_e32 v26, v26
	v_rcp_f32_e32 v27, v27
	v_cvt_pk_bf16_f32 v38, v42, v43
	v_cvt_pk_bf16_f32 v39, v44, v45
	v_cvt_pk_bf16_f32 v40, v50, v51
	v_cvt_pk_bf16_f32 v41, v52, v53
	global_store_dwordx4 v[54:55], v[38:41], off offset:256
	v_mul_f32_e32 v22, 0xbfb8aa3b, v22
	v_mul_f32_e32 v23, 0xbfb8aa3b, v23
	s_waitcnt vmcnt(15)
; #define LAS __attribute__((address_space(3)))
; __device__ __forceinline__ void unpack8(const u32x4 w, float (&v)[8]) { v[0] = bflo(w.x); v[1] = bfhi(w.x); v[2] = bflo(w.y); v[3] = bfhi(w.y); v[4] = bflo(w.z); v[5] = bfhi(w.z); v[6] = bflo(w.w); v[7] = bfhi(w.w); }
; __device__ __forceinline__ u32x4 pack8(const float (&v)[8]) { u32x4 w; w.x = pk2(v[0], v[1]); w.y = pk2(v[2], v[3]); w.z = pk2(v[4], v[5]); w.w = pk2(v[6], v[7]); return w; }
; __device__ __forceinline__ float sigmoidf_(float x) { return __builtin_amdgcn_rcpf(1.0f + __builtin_amdgcn_exp2f(-LOG2E * x)); }
;     __device__ __forceinline__ bool operator()(Acc& acc, const Unit& u, int wr, int wc, int fr, int fq, const LAS float*) const {
;         const size_t o0 = (size_t)(u.pm * BM + wr * 64 + fr) * 512 + u.pn * BM + wc * 32 + 8 * fq; const bf16_t* yp = YS + o0; bf16_t* zp = Z + o0;
;         u32x4 yv[2][4][2];
; #pragma unroll
;         for (int ai = 0; ai < 2; ++ai)
; #pragma unroll
;             for (int m = 0; m < 4; ++m)
; #pragma unroll
;                 for (int bj = 0; bj < 2; ++bj) yv[ai][m][bj] = gld<u32x4>(yp + (ai * HALF + m * 16) * 512 + bj * HALF);
; #pragma unroll
;         for (int ai = 0; ai < 2; ++ai) {
; #pragma unroll
;             for (int m = 0; m < 4; ++m)
; #pragma unroll
;                 for (int bj = 0; bj < 2; ++bj) {
;                     float y[8]; unpack8(yv[ai][m][bj], y);
;                     float v[8];
; #pragma unroll
;                     for (int e = 0; e < 4; ++e) { v[e] = y[e] * sigmoidf_(acc[ai][bj][m][0][e]); v[4 + e] = y[4 + e] * sigmoidf_(acc[ai][bj][m][1][e]); }
;                     gst<u32x4>(zp + (ai * HALF + m * 16) * 512 + bj * HALF, pack8(v));
;                 }
;             asm volatile("" ::: "memory");
;         }
;         return true;
;     }
	v_lshlrev_b32_e32 v38, 16, v70
	v_and_b32_e32 v39, 0xffff0000, v70
	v_pk_mul_f32 v[30:31], v[30:31], v[38:39]
	v_lshlrev_b32_e32 v38, 16, v72
	v_and_b32_e32 v39, 0xffff0000, v72
	v_pk_mul_f32 v[38:39], v[26:27], v[38:39]
	v_mul_f32_e32 v27, 0xbfb8aa3b, v28
	v_exp_f32_e32 v27, v27
	v_mul_f32_e32 v26, 0xbfb8aa3b, v32
	v_exp_f32_e32 v26, v26
	v_lshlrev_b32_e32 v32, 16, v71
	v_add_f32_e32 v27, 1.0, v27
	v_rcp_f32_e32 v28, v27
	v_mul_f32_e32 v27, 0xbfb8aa3b, v33
	v_exp_f32_e32 v27, v27
	v_add_f32_e32 v26, 1.0, v26
	v_rcp_f32_e32 v26, v26
	v_and_b32_e32 v33, 0xffff0000, v71
	v_add_f32_e32 v27, 1.0, v27
	v_rcp_f32_e32 v27, v27
	v_exp_f32_e32 v22, v22
	v_mul_f32_e32 v18, 0xbfb8aa3b, v18
	v_exp_f32_e32 v23, v23
	v_pk_mul_f32 v[32:33], v[26:27], v[32:33]
	v_mul_f32_e32 v26, 0xbfb8aa3b, v29
	v_exp_f32_e32 v26, v26
	v_mul_f32_e32 v19, 0xbfb8aa3b, v19
	v_exp_f32_e32 v18, v18
	v_exp_f32_e32 v19, v19
	v_add_f32_e32 v26, 1.0, v26
	v_rcp_f32_e32 v29, v26
	v_pk_add_f32 v[22:23], v[22:23], 1.0 op_sel_hi:[1,0]
	v_lshlrev_b32_e32 v26, 16, v73
	v_and_b32_e32 v27, 0xffff0000, v73
	v_rcp_f32_e32 v22, v22
	v_pk_add_f32 v[18:19], v[18:19], 1.0 op_sel_hi:[1,0]
	v_rcp_f32_e32 v23, v23
	v_pk_mul_f32 v[40:41], v[28:29], v[26:27]
	v_cvt_pk_bf16_f32 v26, v30, v31
	v_add_co_u32_e32 v30, vcc, s12, v212
	v_rcp_f32_e32 v18, v18
	v_rcp_f32_e32 v19, v19
	v_cvt_pk_bf16_f32 v27, v32, v33
	v_cvt_pk_bf16_f32 v28, v38, v39
	v_cvt_pk_bf16_f32 v29, v40, v41
	v_addc_co_u32_e32 v31, vcc, 0, v213, vcc
	global_store_dwordx4 v[30:31], v[26:29], off
	v_mul_f32_e32 v14, 0xbfb8aa3b, v14
	v_mul_f32_e32 v15, 0xbfb8aa3b, v15
	s_waitcnt vmcnt(15)
	v_lshlrev_b32_e32 v26, 16, v58
	v_and_b32_e32 v27, 0xffff0000, v58
	v_pk_mul_f32 v[22:23], v[22:23], v[26:27]
	v_lshlrev_b32_e32 v26, 16, v60
	v_and_b32_e32 v27, 0xffff0000, v60
	v_pk_mul_f32 v[26:27], v[18:19], v[26:27]
	v_mul_f32_e32 v19, 0xbfb8aa3b, v20
	v_exp_f32_e32 v19, v19
	v_mul_f32_e32 v18, 0xbfb8aa3b, v24
	v_exp_f32_e32 v18, v18
	v_lshlrev_b32_e32 v24, 16, v59
	v_add_f32_e32 v19, 1.0, v19
	v_rcp_f32_e32 v20, v19
	v_mul_f32_e32 v19, 0xbfb8aa3b, v25
	v_exp_f32_e32 v19, v19
	v_add_f32_e32 v18, 1.0, v18
	v_rcp_f32_e32 v18, v18
	v_and_b32_e32 v25, 0xffff0000, v59
	v_add_f32_e32 v19, 1.0, v19
	v_rcp_f32_e32 v19, v19
	v_exp_f32_e32 v14, v14
	v_mul_f32_e32 v10, 0xbfb8aa3b, v10
	v_exp_f32_e32 v15, v15
	v_pk_mul_f32 v[24:25], v[18:19], v[24:25]
	v_mul_f32_e32 v18, 0xbfb8aa3b, v21
	v_exp_f32_e32 v18, v18
	v_mul_f32_e32 v11, 0xbfb8aa3b, v11
	v_exp_f32_e32 v10, v10
	v_exp_f32_e32 v11, v11
	v_add_f32_e32 v18, 1.0, v18
	v_rcp_f32_e32 v21, v18
	v_pk_add_f32 v[14:15], v[14:15], 1.0 op_sel_hi:[1,0]
	v_lshlrev_b32_e32 v18, 16, v61
	v_and_b32_e32 v19, 0xffff0000, v61
	v_rcp_f32_e32 v14, v14
	v_pk_add_f32 v[10:11], v[10:11], 1.0 op_sel_hi:[1,0]
	v_rcp_f32_e32 v15, v15
	v_pk_mul_f32 v[28:29], v[20:21], v[18:19]
	v_rcp_f32_e32 v10, v10
	v_rcp_f32_e32 v11, v11
	v_cvt_pk_bf16_f32 v18, v22, v23
	v_cvt_pk_bf16_f32 v19, v24, v25
	v_cvt_pk_bf16_f32 v20, v26, v27
	v_cvt_pk_bf16_f32 v21, v28, v29
	global_store_dwordx4 v[30:31], v[18:21], off offset:256
	v_mul_f32_e32 v6, 0xbfb8aa3b, v6
	v_mul_f32_e32 v7, 0xbfb8aa3b, v7
	s_waitcnt vmcnt(15)
	v_lshlrev_b32_e32 v18, 16, v46
	v_and_b32_e32 v19, 0xffff0000, v46
	v_pk_mul_f32 v[14:15], v[14:15], v[18:19]
	v_lshlrev_b32_e32 v18, 16, v48
	v_and_b32_e32 v19, 0xffff0000, v48
	v_pk_mul_f32 v[18:19], v[10:11], v[18:19]
	v_mul_f32_e32 v11, 0xbfb8aa3b, v12
	v_exp_f32_e32 v11, v11
	v_mul_f32_e32 v10, 0xbfb8aa3b, v16
	v_exp_f32_e32 v10, v10
	v_lshlrev_b32_e32 v16, 16, v47
	v_add_f32_e32 v11, 1.0, v11
	v_rcp_f32_e32 v12, v11
	v_mul_f32_e32 v11, 0xbfb8aa3b, v17
	v_exp_f32_e32 v11, v11
	v_add_f32_e32 v10, 1.0, v10
	v_rcp_f32_e32 v10, v10
	v_and_b32_e32 v17, 0xffff0000, v47
	v_add_f32_e32 v11, 1.0, v11
	v_rcp_f32_e32 v11, v11
	v_exp_f32_e32 v6, v6
	v_mul_f32_e32 v2, 0xbfb8aa3b, v2
	v_exp_f32_e32 v7, v7
	v_pk_mul_f32 v[16:17], v[10:11], v[16:17]
	v_mul_f32_e32 v10, 0xbfb8aa3b, v13
	v_exp_f32_e32 v10, v10
	v_mul_f32_e32 v3, 0xbfb8aa3b, v3
	v_exp_f32_e32 v2, v2
	v_exp_f32_e32 v3, v3
	v_add_f32_e32 v10, 1.0, v10
	v_rcp_f32_e32 v13, v10
	v_pk_add_f32 v[6:7], v[6:7], 1.0 op_sel_hi:[1,0]
	v_lshlrev_b32_e32 v10, 16, v49
	v_and_b32_e32 v11, 0xffff0000, v49
	v_rcp_f32_e32 v6, v6
	v_pk_add_f32 v[2:3], v[2:3], 1.0 op_sel_hi:[1,0]
	v_rcp_f32_e32 v7, v7
	v_pk_mul_f32 v[20:21], v[12:13], v[10:11]
	v_cvt_pk_bf16_f32 v10, v14, v15
	v_add_co_u32_e32 v14, vcc, s13, v212
	v_rcp_f32_e32 v2, v2
	v_rcp_f32_e32 v3, v3
	v_cvt_pk_bf16_f32 v11, v16, v17
	v_cvt_pk_bf16_f32 v12, v18, v19
	v_cvt_pk_bf16_f32 v13, v20, v21
	v_addc_co_u32_e32 v15, vcc, 0, v213, vcc
	global_store_dwordx4 v[14:15], v[10:13], off
	s_mov_b64 s[8:9], -1
	s_and_b64 vcc, exec, s[4:5]
	s_waitcnt vmcnt(15)
	v_lshlrev_b32_e32 v10, 16, v34
	v_and_b32_e32 v11, 0xffff0000, v34
	v_pk_mul_f32 v[6:7], v[6:7], v[10:11]
	v_lshlrev_b32_e32 v10, 16, v36
	v_and_b32_e32 v11, 0xffff0000, v36
	v_pk_mul_f32 v[10:11], v[2:3], v[10:11]
	v_mul_f32_e32 v3, 0xbfb8aa3b, v4
	v_exp_f32_e32 v3, v3
	v_mul_f32_e32 v2, 0xbfb8aa3b, v8
	v_exp_f32_e32 v2, v2
	v_lshlrev_b32_e32 v8, 16, v35
	v_add_f32_e32 v3, 1.0, v3
	v_rcp_f32_e32 v4, v3
	v_mul_f32_e32 v3, 0xbfb8aa3b, v9
	v_exp_f32_e32 v3, v3
	v_add_f32_e32 v2, 1.0, v2
	v_rcp_f32_e32 v2, v2
	v_and_b32_e32 v9, 0xffff0000, v35
	v_add_f32_e32 v3, 1.0, v3
	v_rcp_f32_e32 v3, v3
	s_nop 0
	v_pk_mul_f32 v[8:9], v[2:3], v[8:9]
	v_mul_f32_e32 v2, 0xbfb8aa3b, v5
	v_exp_f32_e32 v2, v2
	v_and_b32_e32 v3, 0xffff0000, v37
	v_add_f32_e32 v2, 1.0, v2
	v_rcp_f32_e32 v5, v2
	v_lshlrev_b32_e32 v2, 16, v37
	v_pk_mul_f32 v[12:13], v[4:5], v[2:3]
	v_cvt_pk_bf16_f32 v2, v6, v7
	v_cvt_pk_bf16_f32 v3, v8, v9
	v_cvt_pk_bf16_f32 v4, v10, v11
	v_cvt_pk_bf16_f32 v5, v12, v13
	global_store_dwordx4 v[14:15], v[2:5], off offset:256
	s_cbranch_vccnz .LBB0_690
	s_and_b64 vcc, exec, s[0:1]
	s_cbranch_vccnz .LBB0_689
	s_barrier
	s_branch .LBB0_689

; #define LAS __attribute__((address_space(3)))
; __device__ __forceinline__ u32x4 pack8(const float (&v)[8]) { u32x4 w; w.x = pk2(v[0], v[1]); w.y = pk2(v[2], v[3]); w.z = pk2(v[4], v[5]); w.w = pk2(v[6], v[7]); return w; }
;     __device__ __forceinline__ bool operator()(Acc& acc, const Unit& u, int wr, int wc, int fr, int fq, const LAS float* rstab) const {
;         bf16_t* p0 = H + (size_t)(u.pm * BM + wr * 64 + fr) * HD_PITCH + u.pn * HALF + wc * 32 + 8 * fq;
;         const LAS float* rsp = rstab + wr * 64 + fr;
; #pragma unroll
;         for (int ai = 0; ai < 2; ++ai)
; #pragma unroll
;             for (int m = 0; m < 4; ++m) {
;                 const float rs = rsp[ai * HALF + m * 16], nrs = -LOG2E * rs, rs2 = rs * rs;
;                 float v[8];
; #pragma unroll
;                 for (int n = 0; n < 2; ++n)
; #pragma unroll
;                     for (int e = 0; e < 4; ++e) {
;                         const float g = acc[ai][0][m][n][e], up = acc[ai][1][m][n][e];
;                         v[4 * n + e] = (g * up * rs2) * __builtin_amdgcn_rcpf(1.0f + __builtin_amdgcn_exp2f(g * nrs));
;                     }
;                 gst<u32x4>(p0 + (ai * HALF + m * 16) * HD_PITCH, pack8(v));
;                 asm volatile("" ::: "memory");
;             }
;         return true;
;     }
.LBB0_1470:
	v_readlane_b32 s12, v250, 1
	v_and_b32_e32 v0, 15, v2
	s_add_i32 s12, s14, s12
	v_or_b32_e32 v3, s12, v0
	v_readlane_b32 s12, v254, 57
	v_readlane_b32 s13, v254, 58
	v_pk_mul_f32 v[130:131], v[126:127], v[130:131]
	v_pk_mul_f32 v[122:123], v[118:119], v[122:123]
	s_waitcnt lgkmcnt(0)
	v_mov_b64_e32 v[142:143], s[12:13]
	s_movk_i32 s12, 0x1800
	v_mad_i64_i32 v[142:143], s[12:13], v3, s12, v[142:143]
	s_lshl_b32 s12, s52, 7
	s_ashr_i32 s13, s12, 31
	v_lshl_add_u64 v[144:145], s[12:13], 1, v[142:143]
	v_readlane_b32 s12, v250, 11
	v_pk_mul_f32 v[114:115], v[110:111], v[114:115]
	v_pk_mul_f32 v[106:107], v[102:103], v[106:107]
	v_lshl_add_u32 v142, v0, 2, s12
	ds_read_b32 v143, v142
	v_readlane_b32 s12, v254, 33
	s_mov_b32 s14, s12
	v_lshl_add_u64 v[144:145], v[144:145], 0, s[14:15]
	v_and_b32_e32 v0, 48, v2
	s_waitcnt lgkmcnt(0)
	v_mul_f32_e32 v146, 0xbfb8aa3b, v143
	v_pk_mul_f32 v[126:127], v[126:127], v[146:147] op_sel_hi:[1,0]
	v_exp_f32_e32 v126, v126
	v_exp_f32_e32 v127, v127
	v_lshl_add_u64 v[2:3], v[144:145], 0, v[0:1]
	v_mul_f32_e32 v0, v124, v146
	v_exp_f32_e32 v144, v0
	v_mul_f32_e32 v0, v125, v146
	v_exp_f32_e32 v145, v0
	v_mul_f32_e32 v0, v143, v143
	v_pk_mul_f32 v[124:125], v[124:125], v[128:129]
	v_pk_add_f32 v[126:127], v[126:127], 1.0 op_sel_hi:[1,0]
	v_pk_mul_f32 v[128:129], v[130:131], v[0:1] op_sel_hi:[1,0]
	v_pk_mul_f32 v[130:131], v[116:117], v[146:147] op_sel_hi:[1,0]
	v_rcp_f32_e32 v126, v126
	v_rcp_f32_e32 v127, v127
	v_exp_f32_e32 v130, v130
	v_exp_f32_e32 v131, v131
	v_pk_mul_f32 v[118:119], v[118:119], v[146:147] op_sel_hi:[1,0]
	v_exp_f32_e32 v118, v118
	v_exp_f32_e32 v119, v119
	v_add_f32_e32 v143, 1.0, v144
	v_pk_mul_f32 v[126:127], v[128:129], v[126:127]
	v_pk_add_f32 v[128:129], v[130:131], 1.0 op_sel_hi:[1,0]
	v_rcp_f32_e32 v144, v143
	v_add_f32_e32 v143, 1.0, v145
	v_rcp_f32_e32 v128, v128
	v_rcp_f32_e32 v129, v129
	v_pk_add_f32 v[118:119], v[118:119], 1.0 op_sel_hi:[1,0]
	v_rcp_f32_e32 v145, v143
	v_rcp_f32_e32 v118, v118
	v_rcp_f32_e32 v119, v119
	v_pk_mul_f32 v[116:117], v[116:117], v[120:121]
	v_pk_mul_f32 v[124:125], v[124:125], v[0:1] op_sel_hi:[1,0]
	v_pk_mul_f32 v[116:117], v[116:117], v[0:1] op_sel_hi:[1,0]
	v_pk_mul_f32 v[124:125], v[124:125], v[144:145]
	v_pk_mul_f32 v[120:121], v[116:117], v[128:129]
	v_pk_mul_f32 v[116:117], v[122:123], v[0:1] op_sel_hi:[1,0]
	v_readlane_b32 s13, v254, 34
	v_pk_mul_f32 v[122:123], v[116:117], v[118:119]
	v_cvt_pk_bf16_f32 v116, v124, v125
	v_cvt_pk_bf16_f32 v117, v126, v127
	v_cvt_pk_bf16_f32 v118, v120, v121
	v_cvt_pk_bf16_f32 v119, v122, v123
	global_store_dwordx4 v[2:3], v[116:119], off
	ds_read_b32 v0, v142 offset:64
	v_writelane_b32 v254, s12, 33
	v_pk_mul_f32 v[98:99], v[94:95], v[98:99]
	v_pk_mul_f32 v[90:91], v[86:87], v[90:91]
	v_writelane_b32 v254, s13, 34
	s_waitcnt lgkmcnt(0)
	v_mul_f32_e32 v118, 0xbfb8aa3b, v0
	v_pk_mul_f32 v[110:111], v[110:111], v[118:119] op_sel_hi:[1,0]
	v_exp_f32_e32 v110, v110
	v_exp_f32_e32 v111, v111
	v_mul_f32_e32 v0, v0, v0
	v_pk_mul_f32 v[116:117], v[108:109], v[118:119] op_sel_hi:[1,0]
	v_pk_mul_f32 v[108:109], v[108:109], v[112:113]
	v_pk_add_f32 v[110:111], v[110:111], 1.0 op_sel_hi:[1,0]
	v_pk_mul_f32 v[112:113], v[114:115], v[0:1] op_sel_hi:[1,0]
	v_pk_mul_f32 v[114:115], v[100:101], v[118:119] op_sel_hi:[1,0]
	v_rcp_f32_e32 v110, v110
	v_rcp_f32_e32 v111, v111
	v_exp_f32_e32 v114, v114
	v_exp_f32_e32 v115, v115
	v_pk_mul_f32 v[102:103], v[102:103], v[118:119] op_sel_hi:[1,0]
	v_exp_f32_e32 v116, v116
	v_exp_f32_e32 v117, v117
	v_exp_f32_e32 v102, v102
	v_exp_f32_e32 v103, v103
	v_pk_mul_f32 v[110:111], v[112:113], v[110:111]
	v_pk_add_f32 v[112:113], v[114:115], 1.0 op_sel_hi:[1,0]
	v_pk_add_f32 v[116:117], v[116:117], 1.0 op_sel_hi:[1,0]
	v_rcp_f32_e32 v112, v112
	v_rcp_f32_e32 v113, v113
	v_pk_add_f32 v[102:103], v[102:103], 1.0 op_sel_hi:[1,0]
	v_rcp_f32_e32 v116, v116
	v_rcp_f32_e32 v117, v117
	v_rcp_f32_e32 v102, v102
	v_rcp_f32_e32 v103, v103
	v_pk_mul_f32 v[100:101], v[100:101], v[104:105]
	v_pk_mul_f32 v[108:109], v[108:109], v[0:1] op_sel_hi:[1,0]
	v_pk_mul_f32 v[100:101], v[100:101], v[0:1] op_sel_hi:[1,0]
	s_mov_b32 s12, 0x18000
	v_pk_mul_f32 v[104:105], v[100:101], v[112:113]
	v_pk_mul_f32 v[100:101], v[106:107], v[0:1] op_sel_hi:[1,0]
	v_pk_mul_f32 v[108:109], v[108:109], v[116:117]
	v_pk_mul_f32 v[106:107], v[100:101], v[102:103]
	v_cvt_pk_bf16_f32 v102, v104, v105
	v_add_co_u32_e32 v104, vcc, s12, v2
	v_cvt_pk_bf16_f32 v100, v108, v109
	v_cvt_pk_bf16_f32 v101, v110, v111
	v_cvt_pk_bf16_f32 v103, v106, v107
	v_addc_co_u32_e32 v105, vcc, 0, v3, vcc
	global_store_dwordx4 v[104:105], v[100:103], off
	ds_read_b32 v0, v142 offset:128
	s_mov_b32 s12, 0x30000
	v_pk_mul_f32 v[82:83], v[78:79], v[82:83]
	v_pk_mul_f32 v[70:71], v[66:67], v[70:71]
	v_pk_mul_f32 v[58:59], v[54:55], v[58:59]
	s_waitcnt lgkmcnt(0)
; #define LAS __attribute__((address_space(3)))
; __device__ __forceinline__ u32x4 pack8(const float (&v)[8]) { u32x4 w; w.x = pk2(v[0], v[1]); w.y = pk2(v[2], v[3]); w.z = pk2(v[4], v[5]); w.w = pk2(v[6], v[7]); return w; }
;     __device__ __forceinline__ bool operator()(Acc& acc, const Unit& u, int wr, int wc, int fr, int fq, const LAS float* rstab) const {
;         bf16_t* p0 = H + (size_t)(u.pm * BM + wr * 64 + fr) * HD_PITCH + u.pn * HALF + wc * 32 + 8 * fq;
;         const LAS float* rsp = rstab + wr * 64 + fr;
; #pragma unroll
;         for (int ai = 0; ai < 2; ++ai)
; #pragma unroll
;             for (int m = 0; m < 4; ++m) {
;                 const float rs = rsp[ai * HALF + m * 16], nrs = -LOG2E * rs, rs2 = rs * rs;
;                 float v[8];
; #pragma unroll
;                 for (int n = 0; n < 2; ++n)
; #pragma unroll
;                     for (int e = 0; e < 4; ++e) {
;                         const float g = acc[ai][0][m][n][e], up = acc[ai][1][m][n][e];
;                         v[4 * n + e] = (g * up * rs2) * __builtin_amdgcn_rcpf(1.0f + __builtin_amdgcn_exp2f(g * nrs));
;                     }
;                 gst<u32x4>(p0 + (ai * HALF + m * 16) * HD_PITCH, pack8(v));
;                 asm volatile("" ::: "memory");
;             }
;         return true;
;     }
	v_mul_f32_e32 v102, 0xbfb8aa3b, v0
	v_pk_mul_f32 v[94:95], v[94:95], v[102:103] op_sel_hi:[1,0]
	v_exp_f32_e32 v94, v94
	v_exp_f32_e32 v95, v95
	v_mul_f32_e32 v0, v0, v0
	v_pk_mul_f32 v[100:101], v[92:93], v[102:103] op_sel_hi:[1,0]
	v_pk_mul_f32 v[92:93], v[92:93], v[96:97]
	v_pk_add_f32 v[94:95], v[94:95], 1.0 op_sel_hi:[1,0]
	v_pk_mul_f32 v[96:97], v[98:99], v[0:1] op_sel_hi:[1,0]
	v_pk_mul_f32 v[98:99], v[84:85], v[102:103] op_sel_hi:[1,0]
	v_rcp_f32_e32 v94, v94
	v_rcp_f32_e32 v95, v95
	v_exp_f32_e32 v98, v98
	v_exp_f32_e32 v99, v99
	v_pk_mul_f32 v[86:87], v[86:87], v[102:103] op_sel_hi:[1,0]
	v_exp_f32_e32 v100, v100
	v_exp_f32_e32 v101, v101
	v_exp_f32_e32 v86, v86
	v_exp_f32_e32 v87, v87
	v_pk_mul_f32 v[94:95], v[96:97], v[94:95]
	v_pk_add_f32 v[96:97], v[98:99], 1.0 op_sel_hi:[1,0]
	v_pk_add_f32 v[100:101], v[100:101], 1.0 op_sel_hi:[1,0]
	v_rcp_f32_e32 v96, v96
	v_rcp_f32_e32 v97, v97
	v_pk_add_f32 v[86:87], v[86:87], 1.0 op_sel_hi:[1,0]
	v_rcp_f32_e32 v100, v100
	v_rcp_f32_e32 v101, v101
	v_rcp_f32_e32 v86, v86
	v_rcp_f32_e32 v87, v87
	v_pk_mul_f32 v[84:85], v[84:85], v[88:89]
	v_pk_mul_f32 v[92:93], v[92:93], v[0:1] op_sel_hi:[1,0]
	v_pk_mul_f32 v[84:85], v[84:85], v[0:1] op_sel_hi:[1,0]
	v_pk_mul_f32 v[92:93], v[92:93], v[100:101]
	v_pk_mul_f32 v[88:89], v[84:85], v[96:97]
	v_pk_mul_f32 v[84:85], v[90:91], v[0:1] op_sel_hi:[1,0]
	v_pk_mul_f32 v[50:51], v[46:47], v[50:51]
	v_pk_mul_f32 v[90:91], v[84:85], v[86:87]
	v_cvt_pk_bf16_f32 v86, v88, v89
	v_add_co_u32_e32 v88, vcc, s12, v2
	v_cvt_pk_bf16_f32 v84, v92, v93
	v_cvt_pk_bf16_f32 v85, v94, v95
	v_cvt_pk_bf16_f32 v87, v90, v91
	v_addc_co_u32_e32 v89, vcc, 0, v3, vcc
	global_store_dwordx4 v[88:89], v[84:87], off
	ds_read_b32 v0, v142 offset:192
	s_mov_b32 s12, 0x48000
	v_pk_mul_f32 v[42:43], v[38:39], v[42:43]
	v_pk_mul_f32 v[34:35], v[30:31], v[34:35]
	v_pk_mul_f32 v[26:27], v[22:23], v[26:27]
	s_waitcnt lgkmcnt(0)
	v_mul_f32_e32 v86, 0xbfb8aa3b, v0
	v_pk_mul_f32 v[78:79], v[78:79], v[86:87] op_sel_hi:[1,0]
	v_exp_f32_e32 v78, v78
	v_exp_f32_e32 v79, v79
	v_mul_f32_e32 v0, v0, v0
	v_pk_mul_f32 v[84:85], v[76:77], v[86:87] op_sel_hi:[1,0]
	v_pk_mul_f32 v[76:77], v[76:77], v[80:81]
	v_pk_add_f32 v[78:79], v[78:79], 1.0 op_sel_hi:[1,0]
	v_pk_mul_f32 v[80:81], v[82:83], v[0:1] op_sel_hi:[1,0]
	v_pk_mul_f32 v[82:83], v[64:65], v[86:87] op_sel_hi:[1,0]
	v_rcp_f32_e32 v78, v78
	v_rcp_f32_e32 v79, v79
	v_exp_f32_e32 v82, v82
	v_exp_f32_e32 v83, v83
	v_pk_mul_f32 v[66:67], v[66:67], v[86:87] op_sel_hi:[1,0]
	v_exp_f32_e32 v84, v84
	v_exp_f32_e32 v85, v85
	v_exp_f32_e32 v66, v66
	v_exp_f32_e32 v67, v67
	v_pk_mul_f32 v[78:79], v[80:81], v[78:79]
	v_pk_add_f32 v[80:81], v[82:83], 1.0 op_sel_hi:[1,0]
	v_pk_add_f32 v[84:85], v[84:85], 1.0 op_sel_hi:[1,0]
	v_rcp_f32_e32 v80, v80
	v_rcp_f32_e32 v81, v81
	v_pk_add_f32 v[66:67], v[66:67], 1.0 op_sel_hi:[1,0]
	v_rcp_f32_e32 v84, v84
	v_rcp_f32_e32 v85, v85
	v_rcp_f32_e32 v66, v66
	v_rcp_f32_e32 v67, v67
	v_pk_mul_f32 v[64:65], v[64:65], v[68:69]
	v_pk_mul_f32 v[76:77], v[76:77], v[0:1] op_sel_hi:[1,0]
	v_pk_mul_f32 v[64:65], v[64:65], v[0:1] op_sel_hi:[1,0]
	v_pk_mul_f32 v[76:77], v[76:77], v[84:85]
	v_pk_mul_f32 v[68:69], v[64:65], v[80:81]
	v_pk_mul_f32 v[64:65], v[70:71], v[0:1] op_sel_hi:[1,0]
	v_pk_mul_f32 v[18:19], v[14:15], v[18:19]
	v_pk_mul_f32 v[70:71], v[64:65], v[66:67]
	v_cvt_pk_bf16_f32 v66, v68, v69
	v_add_co_u32_e32 v68, vcc, s12, v2
	v_cvt_pk_bf16_f32 v64, v76, v77
	v_cvt_pk_bf16_f32 v65, v78, v79
	v_cvt_pk_bf16_f32 v67, v70, v71
	v_addc_co_u32_e32 v69, vcc, 0, v3, vcc
	global_store_dwordx4 v[68:69], v[64:67], off
	ds_read_b32 v0, v142 offset:512
	s_mov_b32 s12, 0xc0000
	v_pk_mul_f32 v[66:67], v[62:63], v[74:75]
	v_pk_mul_f32 v[10:11], v[6:7], v[10:11]
	s_waitcnt lgkmcnt(0)
	v_mul_f32_e32 v68, 0xbfb8aa3b, v0
	v_pk_mul_f32 v[64:65], v[60:61], v[68:69] op_sel_hi:[1,0]
	v_exp_f32_e32 v64, v64
	v_exp_f32_e32 v65, v65
	v_pk_mul_f32 v[62:63], v[62:63], v[68:69] op_sel_hi:[1,0]
	v_pk_add_f32 v[64:65], v[64:65], 1.0 op_sel_hi:[1,0]
	v_rcp_f32_e32 v64, v64
	v_rcp_f32_e32 v65, v65
	v_exp_f32_e32 v62, v62
	v_exp_f32_e32 v63, v63
	v_mul_f32_e32 v0, v0, v0
	v_pk_mul_f32 v[60:61], v[60:61], v[72:73]
	v_pk_add_f32 v[62:63], v[62:63], 1.0 op_sel_hi:[1,0]
	v_pk_mul_f32 v[60:61], v[60:61], v[0:1] op_sel_hi:[1,0]
	v_pk_mul_f32 v[60:61], v[60:61], v[64:65]
	v_pk_mul_f32 v[64:65], v[66:67], v[0:1] op_sel_hi:[1,0]
	v_pk_mul_f32 v[66:67], v[52:53], v[68:69] op_sel_hi:[1,0]
	v_rcp_f32_e32 v62, v62
	v_rcp_f32_e32 v63, v63
	v_exp_f32_e32 v66, v66
	v_exp_f32_e32 v67, v67
	v_pk_mul_f32 v[54:55], v[54:55], v[68:69] op_sel_hi:[1,0]
	v_exp_f32_e32 v54, v54
	v_exp_f32_e32 v55, v55
	v_pk_mul_f32 v[62:63], v[64:65], v[62:63]
	v_pk_add_f32 v[64:65], v[66:67], 1.0 op_sel_hi:[1,0]
	v_rcp_f32_e32 v64, v64
	v_rcp_f32_e32 v65, v65
	v_pk_add_f32 v[54:55], v[54:55], 1.0 op_sel_hi:[1,0]
	v_rcp_f32_e32 v54, v54
	v_rcp_f32_e32 v55, v55
	v_pk_mul_f32 v[52:53], v[52:53], v[56:57]
	s_nop 0
	v_pk_mul_f32 v[52:53], v[52:53], v[0:1] op_sel_hi:[1,0]
	s_nop 0
	v_pk_mul_f32 v[56:57], v[52:53], v[64:65]
	v_pk_mul_f32 v[52:53], v[58:59], v[0:1] op_sel_hi:[1,0]
	s_nop 0
	v_pk_mul_f32 v[58:59], v[52:53], v[54:55]
	v_cvt_pk_bf16_f32 v54, v56, v57
	v_add_co_u32_e32 v56, vcc, s12, v2
	v_cvt_pk_bf16_f32 v52, v60, v61
	v_cvt_pk_bf16_f32 v53, v62, v63
	v_cvt_pk_bf16_f32 v55, v58, v59
	v_addc_co_u32_e32 v57, vcc, 0, v3, vcc
	global_store_dwordx4 v[56:57], v[52:55], off
	ds_read_b32 v0, v142 offset:576
	s_mov_b32 s12, 0xd8000
	s_waitcnt lgkmcnt(0)
; #define LAS __attribute__((address_space(3)))
; __device__ __forceinline__ u32x4 pack8(const float (&v)[8]) { u32x4 w; w.x = pk2(v[0], v[1]); w.y = pk2(v[2], v[3]); w.z = pk2(v[4], v[5]); w.w = pk2(v[6], v[7]); return w; }
;     __device__ __forceinline__ bool operator()(Acc& acc, const Unit& u, int wr, int wc, int fr, int fq, const LAS float* rstab) const {
;         bf16_t* p0 = H + (size_t)(u.pm * BM + wr * 64 + fr) * HD_PITCH + u.pn * HALF + wc * 32 + 8 * fq;
;         const LAS float* rsp = rstab + wr * 64 + fr;
; #pragma unroll
;         for (int ai = 0; ai < 2; ++ai)
; #pragma unroll
;             for (int m = 0; m < 4; ++m) {
;                 const float rs = rsp[ai * HALF + m * 16], nrs = -LOG2E * rs, rs2 = rs * rs;
;                 float v[8];
; #pragma unroll
;                 for (int n = 0; n < 2; ++n)
; #pragma unroll
;                     for (int e = 0; e < 4; ++e) {
;                         const float g = acc[ai][0][m][n][e], up = acc[ai][1][m][n][e];
;                         v[4 * n + e] = (g * up * rs2) * __builtin_amdgcn_rcpf(1.0f + __builtin_amdgcn_exp2f(g * nrs));
;                     }
;                 gst<u32x4>(p0 + (ai * HALF + m * 16) * HD_PITCH, pack8(v));
;                 asm volatile("" ::: "memory");
;             }
;         return true;
;     }
	v_mul_f32_e32 v54, 0xbfb8aa3b, v0
	v_pk_mul_f32 v[46:47], v[46:47], v[54:55] op_sel_hi:[1,0]
	v_exp_f32_e32 v46, v46
	v_exp_f32_e32 v47, v47
	v_mul_f32_e32 v0, v0, v0
	v_pk_mul_f32 v[52:53], v[44:45], v[54:55] op_sel_hi:[1,0]
	v_pk_mul_f32 v[44:45], v[44:45], v[48:49]
	v_pk_add_f32 v[46:47], v[46:47], 1.0 op_sel_hi:[1,0]
	v_pk_mul_f32 v[48:49], v[50:51], v[0:1] op_sel_hi:[1,0]
	v_pk_mul_f32 v[50:51], v[36:37], v[54:55] op_sel_hi:[1,0]
	v_rcp_f32_e32 v46, v46
	v_rcp_f32_e32 v47, v47
	v_exp_f32_e32 v50, v50
	v_exp_f32_e32 v51, v51
	v_pk_mul_f32 v[38:39], v[38:39], v[54:55] op_sel_hi:[1,0]
	v_exp_f32_e32 v52, v52
	v_exp_f32_e32 v53, v53
	v_exp_f32_e32 v38, v38
	v_exp_f32_e32 v39, v39
	v_pk_mul_f32 v[46:47], v[48:49], v[46:47]
	v_pk_add_f32 v[48:49], v[50:51], 1.0 op_sel_hi:[1,0]
	v_pk_add_f32 v[52:53], v[52:53], 1.0 op_sel_hi:[1,0]
	v_rcp_f32_e32 v48, v48
	v_rcp_f32_e32 v49, v49
	v_pk_add_f32 v[38:39], v[38:39], 1.0 op_sel_hi:[1,0]
	v_rcp_f32_e32 v52, v52
	v_rcp_f32_e32 v53, v53
	v_rcp_f32_e32 v38, v38
	v_rcp_f32_e32 v39, v39
	v_pk_mul_f32 v[36:37], v[36:37], v[40:41]
	v_pk_mul_f32 v[44:45], v[44:45], v[0:1] op_sel_hi:[1,0]
	v_pk_mul_f32 v[36:37], v[36:37], v[0:1] op_sel_hi:[1,0]
	v_pk_mul_f32 v[44:45], v[44:45], v[52:53]
	v_pk_mul_f32 v[40:41], v[36:37], v[48:49]
	v_pk_mul_f32 v[36:37], v[42:43], v[0:1] op_sel_hi:[1,0]
	s_nop 0
	v_pk_mul_f32 v[42:43], v[36:37], v[38:39]
	v_cvt_pk_bf16_f32 v38, v40, v41
	v_add_co_u32_e32 v40, vcc, s12, v2
	v_cvt_pk_bf16_f32 v36, v44, v45
	v_cvt_pk_bf16_f32 v37, v46, v47
	v_cvt_pk_bf16_f32 v39, v42, v43
	v_addc_co_u32_e32 v41, vcc, 0, v3, vcc
	global_store_dwordx4 v[40:41], v[36:39], off
	ds_read_b32 v0, v142 offset:640
	s_mov_b32 s12, 0xf0000
	s_waitcnt lgkmcnt(0)
	v_mul_f32_e32 v38, 0xbfb8aa3b, v0
	v_pk_mul_f32 v[30:31], v[30:31], v[38:39] op_sel_hi:[1,0]
	v_exp_f32_e32 v30, v30
	v_exp_f32_e32 v31, v31
	v_mul_f32_e32 v0, v0, v0
	v_pk_mul_f32 v[36:37], v[28:29], v[38:39] op_sel_hi:[1,0]
	v_pk_mul_f32 v[28:29], v[28:29], v[32:33]
	v_pk_add_f32 v[30:31], v[30:31], 1.0 op_sel_hi:[1,0]
	v_pk_mul_f32 v[32:33], v[34:35], v[0:1] op_sel_hi:[1,0]
	v_pk_mul_f32 v[34:35], v[20:21], v[38:39] op_sel_hi:[1,0]
	v_rcp_f32_e32 v30, v30
	v_rcp_f32_e32 v31, v31
	v_exp_f32_e32 v34, v34
	v_exp_f32_e32 v35, v35
	v_pk_mul_f32 v[22:23], v[22:23], v[38:39] op_sel_hi:[1,0]
	v_exp_f32_e32 v36, v36
	v_exp_f32_e32 v37, v37
	v_exp_f32_e32 v22, v22
	v_exp_f32_e32 v23, v23
	v_pk_mul_f32 v[30:31], v[32:33], v[30:31]
	v_pk_add_f32 v[32:33], v[34:35], 1.0 op_sel_hi:[1,0]
	v_pk_add_f32 v[36:37], v[36:37], 1.0 op_sel_hi:[1,0]
	v_rcp_f32_e32 v32, v32
	v_rcp_f32_e32 v33, v33
	v_pk_add_f32 v[22:23], v[22:23], 1.0 op_sel_hi:[1,0]
	v_rcp_f32_e32 v36, v36
	v_rcp_f32_e32 v37, v37
	v_rcp_f32_e32 v22, v22
	v_rcp_f32_e32 v23, v23
	v_pk_mul_f32 v[20:21], v[20:21], v[24:25]
	v_pk_mul_f32 v[28:29], v[28:29], v[0:1] op_sel_hi:[1,0]
	v_pk_mul_f32 v[20:21], v[20:21], v[0:1] op_sel_hi:[1,0]
	v_pk_mul_f32 v[28:29], v[28:29], v[36:37]
	v_pk_mul_f32 v[24:25], v[20:21], v[32:33]
	v_pk_mul_f32 v[20:21], v[26:27], v[0:1] op_sel_hi:[1,0]
	s_nop 0
	v_pk_mul_f32 v[26:27], v[20:21], v[22:23]
	v_cvt_pk_bf16_f32 v22, v24, v25
	v_add_co_u32_e32 v24, vcc, s12, v2
	v_cvt_pk_bf16_f32 v20, v28, v29
	v_cvt_pk_bf16_f32 v21, v30, v31
	v_cvt_pk_bf16_f32 v23, v26, v27
	v_addc_co_u32_e32 v25, vcc, 0, v3, vcc
	global_store_dwordx4 v[24:25], v[20:23], off
	ds_read_b32 v0, v142 offset:704
	v_add_co_u32_e32 v2, vcc, 0x108000, v2
	s_waitcnt lgkmcnt(0)
	v_mul_f32_e32 v22, 0xbfb8aa3b, v0
	v_pk_mul_f32 v[14:15], v[14:15], v[22:23] op_sel_hi:[1,0]
	v_exp_f32_e32 v14, v14
	v_exp_f32_e32 v15, v15
	v_mul_f32_e32 v0, v0, v0
	v_pk_mul_f32 v[20:21], v[12:13], v[22:23] op_sel_hi:[1,0]
	v_pk_mul_f32 v[12:13], v[12:13], v[16:17]
	v_pk_add_f32 v[14:15], v[14:15], 1.0 op_sel_hi:[1,0]
	v_pk_mul_f32 v[16:17], v[18:19], v[0:1] op_sel_hi:[1,0]
	v_pk_mul_f32 v[18:19], v[4:5], v[22:23] op_sel_hi:[1,0]
	v_rcp_f32_e32 v14, v14
	v_rcp_f32_e32 v15, v15
	v_exp_f32_e32 v18, v18
	v_exp_f32_e32 v19, v19
	v_pk_mul_f32 v[6:7], v[6:7], v[22:23] op_sel_hi:[1,0]
	v_exp_f32_e32 v20, v20
	v_exp_f32_e32 v21, v21
	v_exp_f32_e32 v6, v6
	v_exp_f32_e32 v7, v7
	v_pk_mul_f32 v[14:15], v[16:17], v[14:15]
	v_pk_add_f32 v[16:17], v[18:19], 1.0 op_sel_hi:[1,0]
	v_pk_add_f32 v[20:21], v[20:21], 1.0 op_sel_hi:[1,0]
	v_rcp_f32_e32 v16, v16
	v_rcp_f32_e32 v17, v17
	v_pk_add_f32 v[6:7], v[6:7], 1.0 op_sel_hi:[1,0]
	v_rcp_f32_e32 v20, v20
	v_rcp_f32_e32 v21, v21
	v_rcp_f32_e32 v6, v6
	v_rcp_f32_e32 v7, v7
	v_pk_mul_f32 v[4:5], v[4:5], v[8:9]
	v_pk_mul_f32 v[12:13], v[12:13], v[0:1] op_sel_hi:[1,0]
	v_pk_mul_f32 v[4:5], v[4:5], v[0:1] op_sel_hi:[1,0]
	v_pk_mul_f32 v[12:13], v[12:13], v[20:21]
	v_pk_mul_f32 v[8:9], v[4:5], v[16:17]
	v_pk_mul_f32 v[4:5], v[10:11], v[0:1] op_sel_hi:[1,0]
	v_addc_co_u32_e32 v3, vcc, 0, v3, vcc
	v_pk_mul_f32 v[10:11], v[4:5], v[6:7]
	v_cvt_pk_bf16_f32 v4, v12, v13
	v_cvt_pk_bf16_f32 v5, v14, v15
	v_cvt_pk_bf16_f32 v6, v8, v9
	v_cvt_pk_bf16_f32 v7, v10, v11
	global_store_dwordx4 v[2:3], v[4:7], off
	s_and_b64 vcc, exec, s[2:3]
	s_mov_b64 s[2:3], -1
	s_cbranch_vccnz .LBB0_1453
	v_mov_b32_e32 v225, v198
	v_mov_b64_e32 v[198:199], 0x5bf
	v_mov_b32_e32 v0, 1
	v_mov_b64_e32 v[226:227], 0x5c0
	v_mov_b64_e32 v[246:247], 0xff
	v_mov_b64_e32 v[244:245], 0x100
	s_and_b64 vcc, exec, s[0:1]
	s_cbranch_vccnz .LBB0_1452
	s_barrier
	s_branch .LBB0_1452
